# first load segment's scalar next-tile pointer select chain executed in the shadow of the first MFMA segment
# speedup vs baseline: 1.0025x; 1.0003x over previous
.Lmid1_446:
	s_add_i32 m0, s47, 0xc000
	v_lshl_add_u64 v[162:163], s[56:57], 0, v[156:157]
	global_load_lds_dwordx4 v[162:163], off
	v_lshl_add_u64 v[162:163], v[162:163], 0, s[2:3]
	s_add_i32 m0, s47, 0xe000
	s_nop 0
	global_load_lds_dwordx4 v[162:163], off
	s_waitcnt vmcnt(8) lgkmcnt(0)
	s_barrier
	v_mfma_f32_16x16x32_bf16 v[142:145], v[114:117], v[186:189], 0
	v_mfma_f32_16x16x32_bf16 v[142:145], v[126:129], v[194:197], v[142:145]
	v_mfma_f32_16x16x32_bf16 v[138:141], v[130:133], v[186:189], 0
	v_mfma_f32_16x16x32_bf16 v[138:141], v[134:137], v[194:197], v[138:141]
	v_mfma_f32_16x16x32_bf16 v[110:113], v[114:117], v[198:201], 0
	v_mfma_f32_16x16x32_bf16 v[110:113], v[126:129], v[214:217], v[110:113]
	v_mfma_f32_16x16x32_bf16 v[106:109], v[130:133], v[198:201], 0
	v_mfma_f32_16x16x32_bf16 v[106:109], v[134:137], v[214:217], v[106:109]
	v_mfma_f32_16x16x32_bf16 v[94:97], v[114:117], v[218:221], 0
	v_mfma_f32_16x16x32_bf16 v[94:97], v[126:129], v[222:225], v[94:97]
	v_mfma_f32_16x16x32_bf16 v[90:93], v[130:133], v[218:221], 0
	v_mfma_f32_16x16x32_bf16 v[90:93], v[134:137], v[222:225], v[90:93]
	v_mfma_f32_16x16x32_bf16 v[78:81], v[114:117], v[226:229], 0
	v_mfma_f32_16x16x32_bf16 v[78:81], v[126:129], v[230:233], v[78:81]
	v_mfma_f32_16x16x32_bf16 v[74:77], v[130:133], v[226:229], 0
	v_mfma_f32_16x16x32_bf16 v[74:77], v[134:137], v[230:233], v[74:77]
	s_add_u32 s20, s56, 0xfff50080
	s_addc_u32 s21, s57, -1
	s_cmp_eq_u32 s84, 40
	s_cselect_b32 s61, s49, s21
	s_cselect_b32 s60, s48, s20
	s_cselect_b32 s21, s51, s63
	s_cselect_b32 s20, s50, s62
	v_mfma_f32_16x16x32_bf16 v[122:125], v[146:149], v[186:189], 0
	v_mfma_f32_16x16x32_bf16 v[122:125], v[150:153], v[194:197], v[122:125]
	v_mfma_f32_16x16x32_bf16 v[118:121], v[158:161], v[186:189], 0
	v_mfma_f32_16x16x32_bf16 v[118:121], v[182:185], v[194:197], v[118:121]
	v_mfma_f32_16x16x32_bf16 v[102:105], v[146:149], v[198:201], 0
	v_mfma_f32_16x16x32_bf16 v[102:105], v[150:153], v[214:217], v[102:105]
	v_mfma_f32_16x16x32_bf16 v[98:101], v[158:161], v[198:201], 0
	v_mfma_f32_16x16x32_bf16 v[98:101], v[182:185], v[214:217], v[98:101]
	v_mfma_f32_16x16x32_bf16 v[86:89], v[146:149], v[218:221], 0
	v_mfma_f32_16x16x32_bf16 v[86:89], v[150:153], v[222:225], v[86:89]
	v_mfma_f32_16x16x32_bf16 v[82:85], v[158:161], v[218:221], 0
	v_mfma_f32_16x16x32_bf16 v[82:85], v[182:185], v[222:225], v[82:85]
	v_mfma_f32_16x16x32_bf16 v[70:73], v[146:149], v[226:229], 0
	v_mfma_f32_16x16x32_bf16 v[70:73], v[150:153], v[230:233], v[70:73]
	v_mfma_f32_16x16x32_bf16 v[66:69], v[158:161], v[226:229], 0
	v_mfma_f32_16x16x32_bf16 v[66:69], v[182:185], v[230:233], v[66:69]
	s_barrier
	ds_read_b128 v[186:189], v193 offset:16384
	ds_read_b128 v[194:197], v193 offset:17408
	ds_read_b128 v[198:201], v193 offset:18432
	ds_read_b128 v[214:217], v193 offset:19456
	ds_read_b128 v[218:221], v193 offset:20480
	ds_read_b128 v[222:225], v193 offset:21504
	ds_read_b128 v[226:229], v193 offset:22528
	ds_read_b128 v[230:233], v193 offset:23552
	v_lshl_add_u64 v[162:163], s[20:21], 0, v[0:1]
	s_add_i32 s20, s46, 0x10000
	s_mov_b32 m0, s20
	s_nop 0
	s_nop 0
	global_load_lds_dwordx4 v[162:163], off
	v_lshl_add_u64 v[202:203], v[162:163], 0, s[2:3]
	s_add_i32 m0, s20, 0x2000
	s_add_i32 s20, s46, 0x14000
	global_load_lds_dwordx4 v[202:203], off
	v_lshl_add_u64 v[202:203], v[162:163], 0, s[12:13]
	s_mov_b32 m0, s20
	s_nop 0
	global_load_lds_dwordx4 v[202:203], off
	v_lshl_add_u64 v[202:203], v[162:163], 0, s[86:87]
	s_add_i32 m0, s20, 0x2000
	s_nop 0
	global_load_lds_dwordx4 v[202:203], off
	v_lshl_add_u64 v[202:203], s[60:61], 0, v[154:155]
	s_mov_b32 m0, s47
	v_lshl_add_u64 v[234:235], v[202:203], 0, s[2:3]
	global_load_lds_dwordx4 v[202:203], off
	s_mov_b32 m0, s68
	s_nop 0
	global_load_lds_dwordx4 v[234:235], off
	s_waitcnt vmcnt(8) lgkmcnt(0)
	s_barrier
	v_mfma_f32_16x16x32_bf16 v[62:65], v[114:117], v[186:189], 0
	v_mfma_f32_16x16x32_bf16 v[62:65], v[126:129], v[194:197], v[62:65]
	v_mfma_f32_16x16x32_bf16 v[58:61], v[130:133], v[186:189], 0
	v_mfma_f32_16x16x32_bf16 v[58:61], v[134:137], v[194:197], v[58:61]
	v_mfma_f32_16x16x32_bf16 v[46:49], v[114:117], v[198:201], 0
	v_mfma_f32_16x16x32_bf16 v[46:49], v[126:129], v[214:217], v[46:49]
	v_mfma_f32_16x16x32_bf16 v[42:45], v[130:133], v[198:201], 0
	v_mfma_f32_16x16x32_bf16 v[42:45], v[134:137], v[214:217], v[42:45]
	v_mfma_f32_16x16x32_bf16 v[30:33], v[114:117], v[218:221], 0
	v_mfma_f32_16x16x32_bf16 v[30:33], v[126:129], v[222:225], v[30:33]
	v_mfma_f32_16x16x32_bf16 v[26:29], v[130:133], v[218:221], 0
	v_mfma_f32_16x16x32_bf16 v[26:29], v[134:137], v[222:225], v[26:29]
	v_mfma_f32_16x16x32_bf16 v[14:17], v[114:117], v[226:229], 0
	v_mfma_f32_16x16x32_bf16 v[14:17], v[126:129], v[230:233], v[14:17]
	v_mfma_f32_16x16x32_bf16 v[10:13], v[130:133], v[226:229], 0
	v_mfma_f32_16x16x32_bf16 v[10:13], v[134:137], v[230:233], v[10:13]
	v_mfma_f32_16x16x32_bf16 v[54:57], v[146:149], v[186:189], 0
	v_mfma_f32_16x16x32_bf16 v[54:57], v[150:153], v[194:197], v[54:57]
	v_mfma_f32_16x16x32_bf16 v[50:53], v[158:161], v[186:189], 0
	v_mfma_f32_16x16x32_bf16 v[50:53], v[182:185], v[194:197], v[50:53]
	v_mfma_f32_16x16x32_bf16 v[38:41], v[146:149], v[198:201], 0
	v_mfma_f32_16x16x32_bf16 v[38:41], v[150:153], v[214:217], v[38:41]
	v_mfma_f32_16x16x32_bf16 v[34:37], v[158:161], v[198:201], 0
	v_mfma_f32_16x16x32_bf16 v[34:37], v[182:185], v[214:217], v[34:37]
	v_mfma_f32_16x16x32_bf16 v[22:25], v[146:149], v[218:221], 0
	v_mfma_f32_16x16x32_bf16 v[22:25], v[150:153], v[222:225], v[22:25]
	v_mfma_f32_16x16x32_bf16 v[18:21], v[158:161], v[218:221], 0
	v_mfma_f32_16x16x32_bf16 v[18:21], v[182:185], v[222:225], v[18:21]
	v_mfma_f32_16x16x32_bf16 v[6:9], v[146:149], v[226:229], 0
	v_mfma_f32_16x16x32_bf16 v[6:9], v[150:153], v[230:233], v[6:9]
	v_mfma_f32_16x16x32_bf16 v[2:5], v[158:161], v[226:229], 0
	v_mfma_f32_16x16x32_bf16 v[2:5], v[182:185], v[230:233], v[2:5]
	s_barrier
	ds_read_b128 v[114:117], v243 offset:32768
	ds_read_b128 v[126:129], v243 offset:33792
	ds_read_b128 v[130:133], v243 offset:34816
	ds_read_b128 v[134:137], v243 offset:35840
	ds_read_b128 v[146:149], v243 offset:49152
	ds_read_b128 v[150:153], v243 offset:50176
	ds_read_b128 v[158:161], v243 offset:51200
	ds_read_b128 v[182:185], v243 offset:52224
	ds_read_b128 v[186:189], v193 offset:32768
	ds_read_b128 v[194:197], v193 offset:33792
	ds_read_b128 v[198:201], v193 offset:34816
	ds_read_b128 v[214:217], v193 offset:35840
	ds_read_b128 v[218:221], v193 offset:36864
	ds_read_b128 v[222:225], v193 offset:37888
	ds_read_b128 v[226:229], v193 offset:38912
	ds_read_b128 v[230:233], v193 offset:39936
	s_mov_b32 m0, s69
	v_lshl_add_u64 v[234:235], v[202:203], 0, s[12:13]
	global_load_lds_dwordx4 v[234:235], off
	v_lshl_add_u64 v[234:235], v[202:203], 0, s[86:87]
	s_mov_b32 m0, s76
	s_nop 0
	global_load_lds_dwordx4 v[234:235], off
	s_waitcnt vmcnt(8) lgkmcnt(0)
	s_barrier
	v_mfma_f32_16x16x32_bf16 v[142:145], v[114:117], v[186:189], v[142:145]
	v_mfma_f32_16x16x32_bf16 v[142:145], v[126:129], v[194:197], v[142:145]
	v_mfma_f32_16x16x32_bf16 v[138:141], v[130:133], v[186:189], v[138:141]
	v_mfma_f32_16x16x32_bf16 v[138:141], v[134:137], v[194:197], v[138:141]
	v_mfma_f32_16x16x32_bf16 v[110:113], v[114:117], v[198:201], v[110:113]
	v_mfma_f32_16x16x32_bf16 v[110:113], v[126:129], v[214:217], v[110:113]
	v_mfma_f32_16x16x32_bf16 v[106:109], v[130:133], v[198:201], v[106:109]
	v_mfma_f32_16x16x32_bf16 v[106:109], v[134:137], v[214:217], v[106:109]
	v_mfma_f32_16x16x32_bf16 v[94:97], v[114:117], v[218:221], v[94:97]
	v_mfma_f32_16x16x32_bf16 v[94:97], v[126:129], v[222:225], v[94:97]
	v_mfma_f32_16x16x32_bf16 v[90:93], v[130:133], v[218:221], v[90:93]
	v_mfma_f32_16x16x32_bf16 v[90:93], v[134:137], v[222:225], v[90:93]
	v_mfma_f32_16x16x32_bf16 v[78:81], v[114:117], v[226:229], v[78:81]
	v_mfma_f32_16x16x32_bf16 v[78:81], v[126:129], v[230:233], v[78:81]
	v_mfma_f32_16x16x32_bf16 v[74:77], v[130:133], v[226:229], v[74:77]
	v_mfma_f32_16x16x32_bf16 v[74:77], v[134:137], v[230:233], v[74:77]
	v_mfma_f32_16x16x32_bf16 v[122:125], v[146:149], v[186:189], v[122:125]
	v_mfma_f32_16x16x32_bf16 v[122:125], v[150:153], v[194:197], v[122:125]
	v_mfma_f32_16x16x32_bf16 v[118:121], v[158:161], v[186:189], v[118:121]
	v_mfma_f32_16x16x32_bf16 v[118:121], v[182:185], v[194:197], v[118:121]
	v_mfma_f32_16x16x32_bf16 v[102:105], v[146:149], v[198:201], v[102:105]
	v_mfma_f32_16x16x32_bf16 v[102:105], v[150:153], v[214:217], v[102:105]
	v_mfma_f32_16x16x32_bf16 v[98:101], v[158:161], v[198:201], v[98:101]
	v_mfma_f32_16x16x32_bf16 v[98:101], v[182:185], v[214:217], v[98:101]
	v_mfma_f32_16x16x32_bf16 v[86:89], v[146:149], v[218:221], v[86:89]
	v_mfma_f32_16x16x32_bf16 v[86:89], v[150:153], v[222:225], v[86:89]
	v_mfma_f32_16x16x32_bf16 v[82:85], v[158:161], v[218:221], v[82:85]
	v_mfma_f32_16x16x32_bf16 v[82:85], v[182:185], v[222:225], v[82:85]
	v_mfma_f32_16x16x32_bf16 v[70:73], v[146:149], v[226:229], v[70:73]
	v_mfma_f32_16x16x32_bf16 v[70:73], v[150:153], v[230:233], v[70:73]
	v_mfma_f32_16x16x32_bf16 v[66:69], v[158:161], v[226:229], v[66:69]
	v_mfma_f32_16x16x32_bf16 v[66:69], v[182:185], v[230:233], v[66:69]
	s_barrier
	ds_read_b128 v[186:189], v193 offset:49152
	ds_read_b128 v[194:197], v193 offset:50176
	ds_read_b128 v[198:201], v193 offset:51200
	ds_read_b128 v[214:217], v193 offset:52224
	ds_read_b128 v[218:221], v193 offset:53248
	ds_read_b128 v[222:225], v193 offset:54272
	ds_read_b128 v[226:229], v193 offset:55296
	ds_read_b128 v[230:233], v193 offset:56320
	s_add_i32 s20, s46, 0x18000
	s_mov_b32 m0, s20
	v_lshl_add_u64 v[234:235], v[162:163], 0, s[34:35]
	global_load_lds_dwordx4 v[234:235], off
	v_lshl_add_u64 v[234:235], v[162:163], 0, s[96:97]
	s_add_i32 m0, s20, 0x2000
	s_add_i32 s20, s46, 0x1c000
	global_load_lds_dwordx4 v[234:235], off
	v_lshl_add_u64 v[234:235], v[162:163], 0, vcc
	s_mov_b32 m0, s20
	v_lshl_add_u64 v[162:163], v[162:163], 0, s[0:1]
	global_load_lds_dwordx4 v[234:235], off
	s_add_i32 m0, s20, 0x2000
	s_nop 0
	global_load_lds_dwordx4 v[162:163], off
	v_lshl_add_u64 v[162:163], v[202:203], 0, s[34:35]
	s_mov_b32 m0, s77
	s_nop 0
	global_load_lds_dwordx4 v[162:163], off
	v_lshl_add_u64 v[162:163], v[202:203], 0, s[96:97]
	s_mov_b32 m0, s78
	s_nop 0
	global_load_lds_dwordx4 v[162:163], off
	s_waitcnt vmcnt(8) lgkmcnt(0)
	s_barrier
	v_mfma_f32_16x16x32_bf16 v[62:65], v[114:117], v[186:189], v[62:65]
	v_mfma_f32_16x16x32_bf16 v[62:65], v[126:129], v[194:197], v[62:65]
	v_mfma_f32_16x16x32_bf16 v[58:61], v[130:133], v[186:189], v[58:61]
	v_mfma_f32_16x16x32_bf16 v[58:61], v[134:137], v[194:197], v[58:61]
	v_mfma_f32_16x16x32_bf16 v[46:49], v[114:117], v[198:201], v[46:49]
	v_mfma_f32_16x16x32_bf16 v[46:49], v[126:129], v[214:217], v[46:49]
	v_mfma_f32_16x16x32_bf16 v[42:45], v[130:133], v[198:201], v[42:45]
	v_mfma_f32_16x16x32_bf16 v[42:45], v[134:137], v[214:217], v[42:45]
	v_mfma_f32_16x16x32_bf16 v[30:33], v[114:117], v[218:221], v[30:33]
	v_mfma_f32_16x16x32_bf16 v[30:33], v[126:129], v[222:225], v[30:33]
	v_mfma_f32_16x16x32_bf16 v[26:29], v[130:133], v[218:221], v[26:29]
	v_mfma_f32_16x16x32_bf16 v[26:29], v[134:137], v[222:225], v[26:29]
	v_mfma_f32_16x16x32_bf16 v[14:17], v[114:117], v[226:229], v[14:17]
	v_mfma_f32_16x16x32_bf16 v[14:17], v[126:129], v[230:233], v[14:17]
	v_mfma_f32_16x16x32_bf16 v[10:13], v[130:133], v[226:229], v[10:13]
	v_mfma_f32_16x16x32_bf16 v[10:13], v[134:137], v[230:233], v[10:13]
	s_add_i32 s84, s84, 2
	s_add_u32 s56, s56, 0x100
	s_addc_u32 s57, s57, 0
	s_add_u32 s62, s62, 0x100
	s_addc_u32 s63, s63, 0
	v_mfma_f32_16x16x32_bf16 v[54:57], v[146:149], v[186:189], v[54:57]
	v_mfma_f32_16x16x32_bf16 v[54:57], v[150:153], v[194:197], v[54:57]
	v_mfma_f32_16x16x32_bf16 v[50:53], v[158:161], v[186:189], v[50:53]
	v_mfma_f32_16x16x32_bf16 v[50:53], v[182:185], v[194:197], v[50:53]
	v_mfma_f32_16x16x32_bf16 v[38:41], v[146:149], v[198:201], v[38:41]
	v_mfma_f32_16x16x32_bf16 v[38:41], v[150:153], v[214:217], v[38:41]
	v_mfma_f32_16x16x32_bf16 v[34:37], v[158:161], v[198:201], v[34:37]
	v_mfma_f32_16x16x32_bf16 v[34:37], v[182:185], v[214:217], v[34:37]
	v_mfma_f32_16x16x32_bf16 v[22:25], v[146:149], v[218:221], v[22:25]
	v_mfma_f32_16x16x32_bf16 v[22:25], v[150:153], v[222:225], v[22:25]
	v_mfma_f32_16x16x32_bf16 v[18:21], v[158:161], v[218:221], v[18:21]
	v_mfma_f32_16x16x32_bf16 v[18:21], v[182:185], v[222:225], v[18:21]
	v_mfma_f32_16x16x32_bf16 v[6:9], v[146:149], v[226:229], v[6:9]
	v_mfma_f32_16x16x32_bf16 v[6:9], v[150:153], v[230:233], v[6:9]
	v_mfma_f32_16x16x32_bf16 v[2:5], v[158:161], v[226:229], v[2:5]
	v_mfma_f32_16x16x32_bf16 v[2:5], v[182:185], v[230:233], v[2:5]
	s_barrier
	s_branch .LBB0_446
	.p2alignl 6, 3212836864
.LBB0_446:
	ds_read_b128 v[114:117], v243
	ds_read_b128 v[126:129], v243 offset:1024
	ds_read_b128 v[130:133], v243 offset:2048
	ds_read_b128 v[134:137], v243 offset:3072
	ds_read_b128 v[146:149], v243 offset:16384
	ds_read_b128 v[150:153], v243 offset:17408
	ds_read_b128 v[158:161], v243 offset:18432
	ds_read_b128 v[182:185], v243 offset:19456
	ds_read_b128 v[186:189], v193
	ds_read_b128 v[194:197], v193 offset:1024
	ds_read_b128 v[198:201], v193 offset:2048
	ds_read_b128 v[214:217], v193 offset:3072
	ds_read_b128 v[218:221], v193 offset:4096
	ds_read_b128 v[222:225], v193 offset:5120
	ds_read_b128 v[226:229], v193 offset:6144
	ds_read_b128 v[230:233], v193 offset:7168
	s_add_i32 m0, s47, 0xc000
	v_lshl_add_u64 v[162:163], s[56:57], 0, v[156:157]
	global_load_lds_dwordx4 v[162:163], off
	v_lshl_add_u64 v[162:163], v[162:163], 0, s[2:3]
	s_add_i32 m0, s47, 0xe000
	s_nop 0
	global_load_lds_dwordx4 v[162:163], off
	s_waitcnt vmcnt(8) lgkmcnt(0)
	s_barrier
	v_mfma_f32_16x16x32_bf16 v[142:145], v[114:117], v[186:189], v[142:145]
	v_mfma_f32_16x16x32_bf16 v[142:145], v[126:129], v[194:197], v[142:145]
	v_mfma_f32_16x16x32_bf16 v[138:141], v[130:133], v[186:189], v[138:141]
	v_mfma_f32_16x16x32_bf16 v[138:141], v[134:137], v[194:197], v[138:141]
	v_mfma_f32_16x16x32_bf16 v[110:113], v[114:117], v[198:201], v[110:113]
	v_mfma_f32_16x16x32_bf16 v[110:113], v[126:129], v[214:217], v[110:113]
	v_mfma_f32_16x16x32_bf16 v[106:109], v[130:133], v[198:201], v[106:109]
	v_mfma_f32_16x16x32_bf16 v[106:109], v[134:137], v[214:217], v[106:109]
	v_mfma_f32_16x16x32_bf16 v[94:97], v[114:117], v[218:221], v[94:97]
	v_mfma_f32_16x16x32_bf16 v[94:97], v[126:129], v[222:225], v[94:97]
	v_mfma_f32_16x16x32_bf16 v[90:93], v[130:133], v[218:221], v[90:93]
	v_mfma_f32_16x16x32_bf16 v[90:93], v[134:137], v[222:225], v[90:93]
	v_mfma_f32_16x16x32_bf16 v[78:81], v[114:117], v[226:229], v[78:81]
	v_mfma_f32_16x16x32_bf16 v[78:81], v[126:129], v[230:233], v[78:81]
	v_mfma_f32_16x16x32_bf16 v[74:77], v[130:133], v[226:229], v[74:77]
	v_mfma_f32_16x16x32_bf16 v[74:77], v[134:137], v[230:233], v[74:77]
	s_add_u32 s20, s56, 0xfff50080
	s_addc_u32 s21, s57, -1
	s_cmp_eq_u32 s84, 40
	s_cselect_b32 s61, s49, s21
	s_cselect_b32 s60, s48, s20
	s_cselect_b32 s21, s51, s63
	s_cselect_b32 s20, s50, s62
	v_mfma_f32_16x16x32_bf16 v[122:125], v[146:149], v[186:189], v[122:125]
	v_mfma_f32_16x16x32_bf16 v[122:125], v[150:153], v[194:197], v[122:125]
	v_mfma_f32_16x16x32_bf16 v[118:121], v[158:161], v[186:189], v[118:121]
	v_mfma_f32_16x16x32_bf16 v[118:121], v[182:185], v[194:197], v[118:121]
	v_mfma_f32_16x16x32_bf16 v[102:105], v[146:149], v[198:201], v[102:105]
	v_mfma_f32_16x16x32_bf16 v[102:105], v[150:153], v[214:217], v[102:105]
	v_mfma_f32_16x16x32_bf16 v[98:101], v[158:161], v[198:201], v[98:101]
	v_mfma_f32_16x16x32_bf16 v[98:101], v[182:185], v[214:217], v[98:101]
	v_mfma_f32_16x16x32_bf16 v[86:89], v[146:149], v[218:221], v[86:89]
	v_mfma_f32_16x16x32_bf16 v[86:89], v[150:153], v[222:225], v[86:89]
	v_mfma_f32_16x16x32_bf16 v[82:85], v[158:161], v[218:221], v[82:85]
	v_mfma_f32_16x16x32_bf16 v[82:85], v[182:185], v[222:225], v[82:85]
	v_mfma_f32_16x16x32_bf16 v[70:73], v[146:149], v[226:229], v[70:73]
	v_mfma_f32_16x16x32_bf16 v[70:73], v[150:153], v[230:233], v[70:73]
	v_mfma_f32_16x16x32_bf16 v[66:69], v[158:161], v[226:229], v[66:69]
	v_mfma_f32_16x16x32_bf16 v[66:69], v[182:185], v[230:233], v[66:69]
	s_barrier
	ds_read_b128 v[186:189], v193 offset:16384
	ds_read_b128 v[194:197], v193 offset:17408
	ds_read_b128 v[198:201], v193 offset:18432
	ds_read_b128 v[214:217], v193 offset:19456
	ds_read_b128 v[218:221], v193 offset:20480
	ds_read_b128 v[222:225], v193 offset:21504
	ds_read_b128 v[226:229], v193 offset:22528
	ds_read_b128 v[230:233], v193 offset:23552
	v_lshl_add_u64 v[162:163], s[20:21], 0, v[0:1]
	s_add_i32 s20, s46, 0x10000
	s_mov_b32 m0, s20
	s_nop 0
	s_nop 0
	global_load_lds_dwordx4 v[162:163], off
	v_lshl_add_u64 v[202:203], v[162:163], 0, s[2:3]
	s_add_i32 m0, s20, 0x2000
	s_add_i32 s20, s46, 0x14000
	global_load_lds_dwordx4 v[202:203], off
	v_lshl_add_u64 v[202:203], v[162:163], 0, s[12:13]
	s_mov_b32 m0, s20
	s_nop 0
	global_load_lds_dwordx4 v[202:203], off
	v_lshl_add_u64 v[202:203], v[162:163], 0, s[86:87]
	s_add_i32 m0, s20, 0x2000
	s_nop 0
	global_load_lds_dwordx4 v[202:203], off
	v_lshl_add_u64 v[202:203], s[60:61], 0, v[154:155]
	s_mov_b32 m0, s47
	v_lshl_add_u64 v[234:235], v[202:203], 0, s[2:3]
	global_load_lds_dwordx4 v[202:203], off
	s_mov_b32 m0, s68
	s_nop 0
	global_load_lds_dwordx4 v[234:235], off
	s_waitcnt vmcnt(8) lgkmcnt(0)
	s_barrier
	v_mfma_f32_16x16x32_bf16 v[62:65], v[114:117], v[186:189], v[62:65]
	v_mfma_f32_16x16x32_bf16 v[62:65], v[126:129], v[194:197], v[62:65]
	v_mfma_f32_16x16x32_bf16 v[58:61], v[130:133], v[186:189], v[58:61]
	v_mfma_f32_16x16x32_bf16 v[58:61], v[134:137], v[194:197], v[58:61]
	v_mfma_f32_16x16x32_bf16 v[46:49], v[114:117], v[198:201], v[46:49]
	v_mfma_f32_16x16x32_bf16 v[46:49], v[126:129], v[214:217], v[46:49]
	v_mfma_f32_16x16x32_bf16 v[42:45], v[130:133], v[198:201], v[42:45]
	v_mfma_f32_16x16x32_bf16 v[42:45], v[134:137], v[214:217], v[42:45]
	v_mfma_f32_16x16x32_bf16 v[30:33], v[114:117], v[218:221], v[30:33]
	v_mfma_f32_16x16x32_bf16 v[30:33], v[126:129], v[222:225], v[30:33]
	v_mfma_f32_16x16x32_bf16 v[26:29], v[130:133], v[218:221], v[26:29]
	v_mfma_f32_16x16x32_bf16 v[26:29], v[134:137], v[222:225], v[26:29]
	v_mfma_f32_16x16x32_bf16 v[14:17], v[114:117], v[226:229], v[14:17]
	v_mfma_f32_16x16x32_bf16 v[14:17], v[126:129], v[230:233], v[14:17]
	v_mfma_f32_16x16x32_bf16 v[10:13], v[130:133], v[226:229], v[10:13]
	v_mfma_f32_16x16x32_bf16 v[10:13], v[134:137], v[230:233], v[10:13]
	v_mfma_f32_16x16x32_bf16 v[54:57], v[146:149], v[186:189], v[54:57]
	v_mfma_f32_16x16x32_bf16 v[54:57], v[150:153], v[194:197], v[54:57]
	v_mfma_f32_16x16x32_bf16 v[50:53], v[158:161], v[186:189], v[50:53]
	v_mfma_f32_16x16x32_bf16 v[50:53], v[182:185], v[194:197], v[50:53]
	v_mfma_f32_16x16x32_bf16 v[38:41], v[146:149], v[198:201], v[38:41]
	v_mfma_f32_16x16x32_bf16 v[38:41], v[150:153], v[214:217], v[38:41]
	v_mfma_f32_16x16x32_bf16 v[34:37], v[158:161], v[198:201], v[34:37]
	v_mfma_f32_16x16x32_bf16 v[34:37], v[182:185], v[214:217], v[34:37]
	v_mfma_f32_16x16x32_bf16 v[22:25], v[146:149], v[218:221], v[22:25]
	v_mfma_f32_16x16x32_bf16 v[22:25], v[150:153], v[222:225], v[22:25]
	v_mfma_f32_16x16x32_bf16 v[18:21], v[158:161], v[218:221], v[18:21]
	v_mfma_f32_16x16x32_bf16 v[18:21], v[182:185], v[222:225], v[18:21]
	v_mfma_f32_16x16x32_bf16 v[6:9], v[146:149], v[226:229], v[6:9]
	v_mfma_f32_16x16x32_bf16 v[6:9], v[150:153], v[230:233], v[6:9]
	v_mfma_f32_16x16x32_bf16 v[2:5], v[158:161], v[226:229], v[2:5]
	v_mfma_f32_16x16x32_bf16 v[2:5], v[182:185], v[230:233], v[2:5]
	s_barrier
	ds_read_b128 v[114:117], v243 offset:32768
	ds_read_b128 v[126:129], v243 offset:33792
	ds_read_b128 v[130:133], v243 offset:34816
	ds_read_b128 v[134:137], v243 offset:35840
	ds_read_b128 v[146:149], v243 offset:49152
	ds_read_b128 v[150:153], v243 offset:50176
	ds_read_b128 v[158:161], v243 offset:51200
	ds_read_b128 v[182:185], v243 offset:52224
	ds_read_b128 v[186:189], v193 offset:32768
	ds_read_b128 v[194:197], v193 offset:33792
	ds_read_b128 v[198:201], v193 offset:34816
	ds_read_b128 v[214:217], v193 offset:35840
	ds_read_b128 v[218:221], v193 offset:36864
	ds_read_b128 v[222:225], v193 offset:37888
	ds_read_b128 v[226:229], v193 offset:38912
	ds_read_b128 v[230:233], v193 offset:39936
	s_mov_b32 m0, s69
	v_lshl_add_u64 v[234:235], v[202:203], 0, s[12:13]
	global_load_lds_dwordx4 v[234:235], off
	v_lshl_add_u64 v[234:235], v[202:203], 0, s[86:87]
	s_mov_b32 m0, s76
	s_nop 0
	global_load_lds_dwordx4 v[234:235], off
	s_waitcnt vmcnt(8) lgkmcnt(0)
	s_barrier
	v_mfma_f32_16x16x32_bf16 v[142:145], v[114:117], v[186:189], v[142:145]
	v_mfma_f32_16x16x32_bf16 v[142:145], v[126:129], v[194:197], v[142:145]
	v_mfma_f32_16x16x32_bf16 v[138:141], v[130:133], v[186:189], v[138:141]
	v_mfma_f32_16x16x32_bf16 v[138:141], v[134:137], v[194:197], v[138:141]
	v_mfma_f32_16x16x32_bf16 v[110:113], v[114:117], v[198:201], v[110:113]
	v_mfma_f32_16x16x32_bf16 v[110:113], v[126:129], v[214:217], v[110:113]
	v_mfma_f32_16x16x32_bf16 v[106:109], v[130:133], v[198:201], v[106:109]
	v_mfma_f32_16x16x32_bf16 v[106:109], v[134:137], v[214:217], v[106:109]
	v_mfma_f32_16x16x32_bf16 v[94:97], v[114:117], v[218:221], v[94:97]
	v_mfma_f32_16x16x32_bf16 v[94:97], v[126:129], v[222:225], v[94:97]
	v_mfma_f32_16x16x32_bf16 v[90:93], v[130:133], v[218:221], v[90:93]
	v_mfma_f32_16x16x32_bf16 v[90:93], v[134:137], v[222:225], v[90:93]
	v_mfma_f32_16x16x32_bf16 v[78:81], v[114:117], v[226:229], v[78:81]
	v_mfma_f32_16x16x32_bf16 v[78:81], v[126:129], v[230:233], v[78:81]
	v_mfma_f32_16x16x32_bf16 v[74:77], v[130:133], v[226:229], v[74:77]
	v_mfma_f32_16x16x32_bf16 v[74:77], v[134:137], v[230:233], v[74:77]
	v_mfma_f32_16x16x32_bf16 v[122:125], v[146:149], v[186:189], v[122:125]
	v_mfma_f32_16x16x32_bf16 v[122:125], v[150:153], v[194:197], v[122:125]
	v_mfma_f32_16x16x32_bf16 v[118:121], v[158:161], v[186:189], v[118:121]
	v_mfma_f32_16x16x32_bf16 v[118:121], v[182:185], v[194:197], v[118:121]
	v_mfma_f32_16x16x32_bf16 v[102:105], v[146:149], v[198:201], v[102:105]
	v_mfma_f32_16x16x32_bf16 v[102:105], v[150:153], v[214:217], v[102:105]
	v_mfma_f32_16x16x32_bf16 v[98:101], v[158:161], v[198:201], v[98:101]
	v_mfma_f32_16x16x32_bf16 v[98:101], v[182:185], v[214:217], v[98:101]
	v_mfma_f32_16x16x32_bf16 v[86:89], v[146:149], v[218:221], v[86:89]
	v_mfma_f32_16x16x32_bf16 v[86:89], v[150:153], v[222:225], v[86:89]
	v_mfma_f32_16x16x32_bf16 v[82:85], v[158:161], v[218:221], v[82:85]
	v_mfma_f32_16x16x32_bf16 v[82:85], v[182:185], v[222:225], v[82:85]
	v_mfma_f32_16x16x32_bf16 v[70:73], v[146:149], v[226:229], v[70:73]
	v_mfma_f32_16x16x32_bf16 v[70:73], v[150:153], v[230:233], v[70:73]
	v_mfma_f32_16x16x32_bf16 v[66:69], v[158:161], v[226:229], v[66:69]
	v_mfma_f32_16x16x32_bf16 v[66:69], v[182:185], v[230:233], v[66:69]
	s_barrier
	ds_read_b128 v[186:189], v193 offset:49152
	ds_read_b128 v[194:197], v193 offset:50176
	ds_read_b128 v[198:201], v193 offset:51200
	ds_read_b128 v[214:217], v193 offset:52224
	ds_read_b128 v[218:221], v193 offset:53248
	ds_read_b128 v[222:225], v193 offset:54272
	ds_read_b128 v[226:229], v193 offset:55296
	ds_read_b128 v[230:233], v193 offset:56320
	s_add_i32 s20, s46, 0x18000
	s_mov_b32 m0, s20
	v_lshl_add_u64 v[234:235], v[162:163], 0, s[34:35]
	global_load_lds_dwordx4 v[234:235], off
	v_lshl_add_u64 v[234:235], v[162:163], 0, s[96:97]
	s_add_i32 m0, s20, 0x2000
	s_add_i32 s20, s46, 0x1c000
	global_load_lds_dwordx4 v[234:235], off
	v_lshl_add_u64 v[234:235], v[162:163], 0, vcc
	s_mov_b32 m0, s20
	v_lshl_add_u64 v[162:163], v[162:163], 0, s[0:1]
	global_load_lds_dwordx4 v[234:235], off
	s_add_i32 m0, s20, 0x2000
	s_nop 0
	global_load_lds_dwordx4 v[162:163], off
	v_lshl_add_u64 v[162:163], v[202:203], 0, s[34:35]
	s_mov_b32 m0, s77
	s_nop 0
	global_load_lds_dwordx4 v[162:163], off
	v_lshl_add_u64 v[162:163], v[202:203], 0, s[96:97]
	s_mov_b32 m0, s78
	s_nop 0
	global_load_lds_dwordx4 v[162:163], off
	s_waitcnt vmcnt(8) lgkmcnt(0)
	s_barrier
	v_mfma_f32_16x16x32_bf16 v[62:65], v[114:117], v[186:189], v[62:65]
	v_mfma_f32_16x16x32_bf16 v[62:65], v[126:129], v[194:197], v[62:65]
	v_mfma_f32_16x16x32_bf16 v[58:61], v[130:133], v[186:189], v[58:61]
	v_mfma_f32_16x16x32_bf16 v[58:61], v[134:137], v[194:197], v[58:61]
	v_mfma_f32_16x16x32_bf16 v[46:49], v[114:117], v[198:201], v[46:49]
	v_mfma_f32_16x16x32_bf16 v[46:49], v[126:129], v[214:217], v[46:49]
	v_mfma_f32_16x16x32_bf16 v[42:45], v[130:133], v[198:201], v[42:45]
	v_mfma_f32_16x16x32_bf16 v[42:45], v[134:137], v[214:217], v[42:45]
	v_mfma_f32_16x16x32_bf16 v[30:33], v[114:117], v[218:221], v[30:33]
	v_mfma_f32_16x16x32_bf16 v[30:33], v[126:129], v[222:225], v[30:33]
	v_mfma_f32_16x16x32_bf16 v[26:29], v[130:133], v[218:221], v[26:29]
	v_mfma_f32_16x16x32_bf16 v[26:29], v[134:137], v[222:225], v[26:29]
	v_mfma_f32_16x16x32_bf16 v[14:17], v[114:117], v[226:229], v[14:17]
	v_mfma_f32_16x16x32_bf16 v[14:17], v[126:129], v[230:233], v[14:17]
	v_mfma_f32_16x16x32_bf16 v[10:13], v[130:133], v[226:229], v[10:13]
	v_mfma_f32_16x16x32_bf16 v[10:13], v[134:137], v[230:233], v[10:13]
	s_add_i32 s84, s84, 2
	s_add_u32 s56, s56, 0x100
	s_addc_u32 s57, s57, 0
	s_add_u32 s62, s62, 0x100
	s_addc_u32 s63, s63, 0
	v_mfma_f32_16x16x32_bf16 v[54:57], v[146:149], v[186:189], v[54:57]
	v_mfma_f32_16x16x32_bf16 v[54:57], v[150:153], v[194:197], v[54:57]
	v_mfma_f32_16x16x32_bf16 v[50:53], v[158:161], v[186:189], v[50:53]
	v_mfma_f32_16x16x32_bf16 v[50:53], v[182:185], v[194:197], v[50:53]
	v_mfma_f32_16x16x32_bf16 v[38:41], v[146:149], v[198:201], v[38:41]
	v_mfma_f32_16x16x32_bf16 v[38:41], v[150:153], v[214:217], v[38:41]
	v_mfma_f32_16x16x32_bf16 v[34:37], v[158:161], v[198:201], v[34:37]
	v_mfma_f32_16x16x32_bf16 v[34:37], v[182:185], v[214:217], v[34:37]
	v_mfma_f32_16x16x32_bf16 v[22:25], v[146:149], v[218:221], v[22:25]
	v_mfma_f32_16x16x32_bf16 v[22:25], v[150:153], v[222:225], v[22:25]
	v_mfma_f32_16x16x32_bf16 v[18:21], v[158:161], v[218:221], v[18:21]
	v_mfma_f32_16x16x32_bf16 v[18:21], v[182:185], v[222:225], v[18:21]
	v_mfma_f32_16x16x32_bf16 v[6:9], v[146:149], v[226:229], v[6:9]
	v_mfma_f32_16x16x32_bf16 v[6:9], v[150:153], v[230:233], v[6:9]
	v_mfma_f32_16x16x32_bf16 v[2:5], v[158:161], v[226:229], v[2:5]
	v_mfma_f32_16x16x32_bf16 v[2:5], v[182:185], v[230:233], v[2:5]
	s_barrier
	s_cmp_gt_u32 s84, 41
	s_cbranch_scc0 .LBB0_446
	s_setprio 0
	s_and_b64 vcc, exec, s[40:41]
	s_cbranch_vccz .LBB0_449
	s_barrier

.Lmid1_488:
	s_add_i32 m0, s43, 0xc000
	v_lshl_add_u64 v[202:203], s[68:69], 0, v[132:133]
	global_load_lds_dwordx4 v[202:203], off
	v_lshl_add_u64 v[202:203], v[202:203], 0, s[72:73]
	s_add_i32 m0, s43, 0xe000
	s_nop 0
	global_load_lds_dwordx4 v[202:203], off
	s_waitcnt vmcnt(8) lgkmcnt(0)
	s_barrier
	v_mfma_f32_16x16x32_bf16 v[126:129], v[134:137], v[190:193], 0
	v_mfma_f32_16x16x32_bf16 v[126:129], v[144:147], v[194:197], v[126:129]
	v_mfma_f32_16x16x32_bf16 v[114:117], v[148:151], v[190:193], 0
	v_mfma_f32_16x16x32_bf16 v[114:117], v[152:155], v[194:197], v[114:117]
	v_mfma_f32_16x16x32_bf16 v[110:113], v[134:137], v[198:201], 0
	v_mfma_f32_16x16x32_bf16 v[110:113], v[144:147], v[214:217], v[110:113]
	v_mfma_f32_16x16x32_bf16 v[98:101], v[148:151], v[198:201], 0
	v_mfma_f32_16x16x32_bf16 v[98:101], v[152:155], v[214:217], v[98:101]
	v_mfma_f32_16x16x32_bf16 v[94:97], v[134:137], v[218:221], 0
	v_mfma_f32_16x16x32_bf16 v[94:97], v[144:147], v[222:225], v[94:97]
	v_mfma_f32_16x16x32_bf16 v[82:85], v[148:151], v[218:221], 0
	v_mfma_f32_16x16x32_bf16 v[82:85], v[152:155], v[222:225], v[82:85]
	v_mfma_f32_16x16x32_bf16 v[78:81], v[134:137], v[226:229], 0
	v_mfma_f32_16x16x32_bf16 v[78:81], v[144:147], v[230:233], v[78:81]
	v_mfma_f32_16x16x32_bf16 v[66:69], v[148:151], v[226:229], 0
	v_mfma_f32_16x16x32_bf16 v[66:69], v[152:155], v[230:233], v[66:69]
	s_add_u32 s20, s68, 0xfffc0080
	s_addc_u32 s21, s69, -1
	s_cmp_eq_u32 s97, 12
	s_cselect_b32 s77, s57, s21
	s_cselect_b32 s76, s86, s20
	s_cselect_b32 s21, s51, s96
	s_cselect_b32 s20, s87, s91
	v_mfma_f32_16x16x32_bf16 v[122:125], v[156:159], v[190:193], 0
	v_mfma_f32_16x16x32_bf16 v[122:125], v[160:163], v[194:197], v[122:125]
	v_mfma_f32_16x16x32_bf16 v[118:121], v[182:185], v[190:193], 0
	v_mfma_f32_16x16x32_bf16 v[118:121], v[186:189], v[194:197], v[118:121]
	v_mfma_f32_16x16x32_bf16 v[106:109], v[156:159], v[198:201], 0
	v_mfma_f32_16x16x32_bf16 v[106:109], v[160:163], v[214:217], v[106:109]
	v_mfma_f32_16x16x32_bf16 v[102:105], v[182:185], v[198:201], 0
	v_mfma_f32_16x16x32_bf16 v[102:105], v[186:189], v[214:217], v[102:105]
	v_mfma_f32_16x16x32_bf16 v[90:93], v[156:159], v[218:221], 0
	v_mfma_f32_16x16x32_bf16 v[90:93], v[160:163], v[222:225], v[90:93]
	v_mfma_f32_16x16x32_bf16 v[86:89], v[182:185], v[218:221], 0
	v_mfma_f32_16x16x32_bf16 v[86:89], v[186:189], v[222:225], v[86:89]
	v_mfma_f32_16x16x32_bf16 v[74:77], v[156:159], v[226:229], 0
	v_mfma_f32_16x16x32_bf16 v[74:77], v[160:163], v[230:233], v[74:77]
	v_mfma_f32_16x16x32_bf16 v[70:73], v[182:185], v[226:229], 0
	v_mfma_f32_16x16x32_bf16 v[70:73], v[186:189], v[230:233], v[70:73]
	s_barrier
	ds_read_b128 v[190:193], v142 offset:16384
	ds_read_b128 v[194:197], v142 offset:17408
	ds_read_b128 v[198:201], v142 offset:18432
	ds_read_b128 v[214:217], v142 offset:19456
	ds_read_b128 v[218:221], v142 offset:20480
	ds_read_b128 v[222:225], v142 offset:21504
	ds_read_b128 v[226:229], v142 offset:22528
	ds_read_b128 v[230:233], v142 offset:23552
	v_lshl_add_u64 v[202:203], s[20:21], 0, v[0:1]
	s_add_i32 s20, s14, 0x10000
	s_mov_b32 m0, s20
	s_nop 0
	s_nop 0
	global_load_lds_dwordx4 v[202:203], off
	v_lshl_add_u64 v[234:235], v[202:203], 0, s[72:73]
	s_add_i32 m0, s20, 0x2000
	s_add_i32 s20, s14, 0x14000
	global_load_lds_dwordx4 v[234:235], off
	v_lshl_add_u64 v[234:235], v[202:203], 0, s[28:29]
	s_mov_b32 m0, s20
	s_nop 0
	global_load_lds_dwordx4 v[234:235], off
	v_lshl_add_u64 v[234:235], v[202:203], 0, s[82:83]
	s_add_i32 m0, s20, 0x2000
	s_nop 0
	global_load_lds_dwordx4 v[234:235], off
	v_lshl_add_u64 v[234:235], s[76:77], 0, v[130:131]
	s_mov_b32 m0, s43
	v_lshl_add_u64 v[236:237], v[234:235], 0, s[72:73]
	global_load_lds_dwordx4 v[234:235], off
	s_mov_b32 m0, s46
	s_nop 0
	global_load_lds_dwordx4 v[236:237], off
	s_waitcnt vmcnt(8) lgkmcnt(0)
	s_barrier
	v_mfma_f32_16x16x32_bf16 v[62:65], v[134:137], v[190:193], 0
	v_mfma_f32_16x16x32_bf16 v[62:65], v[144:147], v[194:197], v[62:65]
	v_mfma_f32_16x16x32_bf16 v[50:53], v[148:151], v[190:193], 0
	v_mfma_f32_16x16x32_bf16 v[50:53], v[152:155], v[194:197], v[50:53]
	v_mfma_f32_16x16x32_bf16 v[46:49], v[134:137], v[198:201], 0
	v_mfma_f32_16x16x32_bf16 v[46:49], v[144:147], v[214:217], v[46:49]
	v_mfma_f32_16x16x32_bf16 v[34:37], v[148:151], v[198:201], 0
	v_mfma_f32_16x16x32_bf16 v[34:37], v[152:155], v[214:217], v[34:37]
	v_mfma_f32_16x16x32_bf16 v[30:33], v[134:137], v[218:221], 0
	v_mfma_f32_16x16x32_bf16 v[30:33], v[144:147], v[222:225], v[30:33]
	v_mfma_f32_16x16x32_bf16 v[18:21], v[148:151], v[218:221], 0
	v_mfma_f32_16x16x32_bf16 v[18:21], v[152:155], v[222:225], v[18:21]
	v_mfma_f32_16x16x32_bf16 v[14:17], v[134:137], v[226:229], 0
	v_mfma_f32_16x16x32_bf16 v[14:17], v[144:147], v[230:233], v[14:17]
	v_mfma_f32_16x16x32_bf16 v[6:9], v[148:151], v[226:229], 0
	v_mfma_f32_16x16x32_bf16 v[6:9], v[152:155], v[230:233], v[6:9]
	v_mfma_f32_16x16x32_bf16 v[58:61], v[156:159], v[190:193], 0
	v_mfma_f32_16x16x32_bf16 v[58:61], v[160:163], v[194:197], v[58:61]
	v_mfma_f32_16x16x32_bf16 v[54:57], v[182:185], v[190:193], 0
	v_mfma_f32_16x16x32_bf16 v[54:57], v[186:189], v[194:197], v[54:57]
	v_mfma_f32_16x16x32_bf16 v[42:45], v[156:159], v[198:201], 0
	v_mfma_f32_16x16x32_bf16 v[42:45], v[160:163], v[214:217], v[42:45]
	v_mfma_f32_16x16x32_bf16 v[38:41], v[182:185], v[198:201], 0
	v_mfma_f32_16x16x32_bf16 v[38:41], v[186:189], v[214:217], v[38:41]
	v_mfma_f32_16x16x32_bf16 v[26:29], v[156:159], v[218:221], 0
	v_mfma_f32_16x16x32_bf16 v[26:29], v[160:163], v[222:225], v[26:29]
	v_mfma_f32_16x16x32_bf16 v[22:25], v[182:185], v[218:221], 0
	v_mfma_f32_16x16x32_bf16 v[22:25], v[186:189], v[222:225], v[22:25]
	v_mfma_f32_16x16x32_bf16 v[10:13], v[156:159], v[226:229], 0
	v_mfma_f32_16x16x32_bf16 v[10:13], v[160:163], v[230:233], v[10:13]
	v_mfma_f32_16x16x32_bf16 v[2:5], v[182:185], v[226:229], 0
	v_mfma_f32_16x16x32_bf16 v[2:5], v[186:189], v[230:233], v[2:5]
	s_barrier
	ds_read_b128 v[134:137], v243 offset:32768
	ds_read_b128 v[144:147], v243 offset:33792
	ds_read_b128 v[148:151], v243 offset:34816
	ds_read_b128 v[152:155], v243 offset:35840
	ds_read_b128 v[156:159], v243 offset:49152
	ds_read_b128 v[160:163], v243 offset:50176
	ds_read_b128 v[182:185], v243 offset:51200
	ds_read_b128 v[186:189], v243 offset:52224
	ds_read_b128 v[190:193], v142 offset:32768
	ds_read_b128 v[194:197], v142 offset:33792
	ds_read_b128 v[198:201], v142 offset:34816
	ds_read_b128 v[214:217], v142 offset:35840
	ds_read_b128 v[218:221], v142 offset:36864
	ds_read_b128 v[222:225], v142 offset:37888
	ds_read_b128 v[226:229], v142 offset:38912
	ds_read_b128 v[230:233], v142 offset:39936
	s_mov_b32 m0, s47
	v_lshl_add_u64 v[236:237], v[234:235], 0, s[28:29]
	global_load_lds_dwordx4 v[236:237], off
	v_lshl_add_u64 v[236:237], v[234:235], 0, s[82:83]
	s_mov_b32 m0, s78
	s_nop 0
	global_load_lds_dwordx4 v[236:237], off
	s_waitcnt vmcnt(8) lgkmcnt(0)
	s_barrier
	v_mfma_f32_16x16x32_bf16 v[126:129], v[134:137], v[190:193], v[126:129]
	v_mfma_f32_16x16x32_bf16 v[126:129], v[144:147], v[194:197], v[126:129]
	v_mfma_f32_16x16x32_bf16 v[114:117], v[148:151], v[190:193], v[114:117]
	v_mfma_f32_16x16x32_bf16 v[114:117], v[152:155], v[194:197], v[114:117]
	v_mfma_f32_16x16x32_bf16 v[110:113], v[134:137], v[198:201], v[110:113]
	v_mfma_f32_16x16x32_bf16 v[110:113], v[144:147], v[214:217], v[110:113]
	v_mfma_f32_16x16x32_bf16 v[98:101], v[148:151], v[198:201], v[98:101]
	v_mfma_f32_16x16x32_bf16 v[98:101], v[152:155], v[214:217], v[98:101]
	v_mfma_f32_16x16x32_bf16 v[94:97], v[134:137], v[218:221], v[94:97]
	v_mfma_f32_16x16x32_bf16 v[94:97], v[144:147], v[222:225], v[94:97]
	v_mfma_f32_16x16x32_bf16 v[82:85], v[148:151], v[218:221], v[82:85]
	v_mfma_f32_16x16x32_bf16 v[82:85], v[152:155], v[222:225], v[82:85]
	v_mfma_f32_16x16x32_bf16 v[78:81], v[134:137], v[226:229], v[78:81]
	v_mfma_f32_16x16x32_bf16 v[78:81], v[144:147], v[230:233], v[78:81]
	v_mfma_f32_16x16x32_bf16 v[66:69], v[148:151], v[226:229], v[66:69]
	v_mfma_f32_16x16x32_bf16 v[66:69], v[152:155], v[230:233], v[66:69]
	v_mfma_f32_16x16x32_bf16 v[122:125], v[156:159], v[190:193], v[122:125]
	v_mfma_f32_16x16x32_bf16 v[122:125], v[160:163], v[194:197], v[122:125]
	v_mfma_f32_16x16x32_bf16 v[118:121], v[182:185], v[190:193], v[118:121]
	v_mfma_f32_16x16x32_bf16 v[118:121], v[186:189], v[194:197], v[118:121]
	v_mfma_f32_16x16x32_bf16 v[106:109], v[156:159], v[198:201], v[106:109]
	v_mfma_f32_16x16x32_bf16 v[106:109], v[160:163], v[214:217], v[106:109]
	v_mfma_f32_16x16x32_bf16 v[102:105], v[182:185], v[198:201], v[102:105]
	v_mfma_f32_16x16x32_bf16 v[102:105], v[186:189], v[214:217], v[102:105]
	v_mfma_f32_16x16x32_bf16 v[90:93], v[156:159], v[218:221], v[90:93]
	v_mfma_f32_16x16x32_bf16 v[90:93], v[160:163], v[222:225], v[90:93]
	v_mfma_f32_16x16x32_bf16 v[86:89], v[182:185], v[218:221], v[86:89]
	v_mfma_f32_16x16x32_bf16 v[86:89], v[186:189], v[222:225], v[86:89]
	v_mfma_f32_16x16x32_bf16 v[74:77], v[156:159], v[226:229], v[74:77]
	v_mfma_f32_16x16x32_bf16 v[74:77], v[160:163], v[230:233], v[74:77]
	v_mfma_f32_16x16x32_bf16 v[70:73], v[182:185], v[226:229], v[70:73]
	v_mfma_f32_16x16x32_bf16 v[70:73], v[186:189], v[230:233], v[70:73]
	s_barrier
	ds_read_b128 v[190:193], v142 offset:49152
	ds_read_b128 v[194:197], v142 offset:50176
	ds_read_b128 v[198:201], v142 offset:51200
	ds_read_b128 v[214:217], v142 offset:52224
	ds_read_b128 v[218:221], v142 offset:53248
	ds_read_b128 v[222:225], v142 offset:54272
	ds_read_b128 v[226:229], v142 offset:55296
	ds_read_b128 v[230:233], v142 offset:56320
	s_add_i32 s20, s14, 0x18000
	s_mov_b32 m0, s20
	v_lshl_add_u64 v[236:237], v[202:203], 0, s[34:35]
	global_load_lds_dwordx4 v[236:237], off
	v_lshl_add_u64 v[236:237], v[202:203], 0, s[38:39]
	s_add_i32 m0, s20, 0x2000
	s_add_i32 s20, s14, 0x1c000
	global_load_lds_dwordx4 v[236:237], off
	v_lshl_add_u64 v[236:237], v[202:203], 0, s[44:45]
	s_mov_b32 m0, s20
	v_lshl_add_u64 v[202:203], v[202:203], 0, s[10:11]
	global_load_lds_dwordx4 v[236:237], off
	s_add_i32 m0, s20, 0x2000
	s_nop 0
	global_load_lds_dwordx4 v[202:203], off
	v_lshl_add_u64 v[202:203], v[234:235], 0, s[34:35]
	s_mov_b32 m0, s79
	s_nop 0
	global_load_lds_dwordx4 v[202:203], off
	v_lshl_add_u64 v[202:203], v[234:235], 0, s[38:39]
	s_mov_b32 m0, s88
	s_nop 0
	global_load_lds_dwordx4 v[202:203], off
	s_waitcnt vmcnt(8) lgkmcnt(0)
	s_barrier
	v_mfma_f32_16x16x32_bf16 v[62:65], v[134:137], v[190:193], v[62:65]
	v_mfma_f32_16x16x32_bf16 v[62:65], v[144:147], v[194:197], v[62:65]
	v_mfma_f32_16x16x32_bf16 v[50:53], v[148:151], v[190:193], v[50:53]
	v_mfma_f32_16x16x32_bf16 v[50:53], v[152:155], v[194:197], v[50:53]
	v_mfma_f32_16x16x32_bf16 v[46:49], v[134:137], v[198:201], v[46:49]
	v_mfma_f32_16x16x32_bf16 v[46:49], v[144:147], v[214:217], v[46:49]
	v_mfma_f32_16x16x32_bf16 v[34:37], v[148:151], v[198:201], v[34:37]
	v_mfma_f32_16x16x32_bf16 v[34:37], v[152:155], v[214:217], v[34:37]
	v_mfma_f32_16x16x32_bf16 v[30:33], v[134:137], v[218:221], v[30:33]
	v_mfma_f32_16x16x32_bf16 v[30:33], v[144:147], v[222:225], v[30:33]
	v_mfma_f32_16x16x32_bf16 v[18:21], v[148:151], v[218:221], v[18:21]
	v_mfma_f32_16x16x32_bf16 v[18:21], v[152:155], v[222:225], v[18:21]
	v_mfma_f32_16x16x32_bf16 v[14:17], v[134:137], v[226:229], v[14:17]
	v_mfma_f32_16x16x32_bf16 v[14:17], v[144:147], v[230:233], v[14:17]
	v_mfma_f32_16x16x32_bf16 v[6:9], v[148:151], v[226:229], v[6:9]
	v_mfma_f32_16x16x32_bf16 v[6:9], v[152:155], v[230:233], v[6:9]
	s_add_i32 s97, s97, 2
	s_add_u32 s68, s68, 0x100
	s_addc_u32 s69, s69, 0
	s_add_u32 s91, s91, 0x100
	s_addc_u32 s96, s96, 0
	v_mfma_f32_16x16x32_bf16 v[58:61], v[156:159], v[190:193], v[58:61]
	v_mfma_f32_16x16x32_bf16 v[58:61], v[160:163], v[194:197], v[58:61]
	v_mfma_f32_16x16x32_bf16 v[54:57], v[182:185], v[190:193], v[54:57]
	v_mfma_f32_16x16x32_bf16 v[54:57], v[186:189], v[194:197], v[54:57]
	v_mfma_f32_16x16x32_bf16 v[42:45], v[156:159], v[198:201], v[42:45]
	v_mfma_f32_16x16x32_bf16 v[42:45], v[160:163], v[214:217], v[42:45]
	v_mfma_f32_16x16x32_bf16 v[38:41], v[182:185], v[198:201], v[38:41]
	v_mfma_f32_16x16x32_bf16 v[38:41], v[186:189], v[214:217], v[38:41]
	v_mfma_f32_16x16x32_bf16 v[26:29], v[156:159], v[218:221], v[26:29]
	v_mfma_f32_16x16x32_bf16 v[26:29], v[160:163], v[222:225], v[26:29]
	v_mfma_f32_16x16x32_bf16 v[22:25], v[182:185], v[218:221], v[22:25]
	v_mfma_f32_16x16x32_bf16 v[22:25], v[186:189], v[222:225], v[22:25]
	v_mfma_f32_16x16x32_bf16 v[10:13], v[156:159], v[226:229], v[10:13]
	v_mfma_f32_16x16x32_bf16 v[10:13], v[160:163], v[230:233], v[10:13]
	v_mfma_f32_16x16x32_bf16 v[2:5], v[182:185], v[226:229], v[2:5]
	v_mfma_f32_16x16x32_bf16 v[2:5], v[186:189], v[230:233], v[2:5]
	s_barrier
	s_branch .LBB0_488
	.p2alignl 6, 3212836864
.LBB0_488:
	ds_read_b128 v[134:137], v243
	ds_read_b128 v[144:147], v243 offset:1024
	ds_read_b128 v[148:151], v243 offset:2048
	ds_read_b128 v[152:155], v243 offset:3072
	ds_read_b128 v[156:159], v243 offset:16384
	ds_read_b128 v[160:163], v243 offset:17408
	ds_read_b128 v[182:185], v243 offset:18432
	ds_read_b128 v[186:189], v243 offset:19456
	ds_read_b128 v[190:193], v142
	ds_read_b128 v[194:197], v142 offset:1024
	ds_read_b128 v[198:201], v142 offset:2048
	ds_read_b128 v[214:217], v142 offset:3072
	ds_read_b128 v[218:221], v142 offset:4096
	ds_read_b128 v[222:225], v142 offset:5120
	ds_read_b128 v[226:229], v142 offset:6144
	ds_read_b128 v[230:233], v142 offset:7168
	s_add_i32 m0, s43, 0xc000
	v_lshl_add_u64 v[202:203], s[68:69], 0, v[132:133]
	global_load_lds_dwordx4 v[202:203], off
	v_lshl_add_u64 v[202:203], v[202:203], 0, s[72:73]
	s_add_i32 m0, s43, 0xe000
	s_nop 0
	global_load_lds_dwordx4 v[202:203], off
	s_waitcnt vmcnt(8) lgkmcnt(0)
	s_barrier
	v_mfma_f32_16x16x32_bf16 v[126:129], v[134:137], v[190:193], v[126:129]
	v_mfma_f32_16x16x32_bf16 v[126:129], v[144:147], v[194:197], v[126:129]
	v_mfma_f32_16x16x32_bf16 v[114:117], v[148:151], v[190:193], v[114:117]
	v_mfma_f32_16x16x32_bf16 v[114:117], v[152:155], v[194:197], v[114:117]
	v_mfma_f32_16x16x32_bf16 v[110:113], v[134:137], v[198:201], v[110:113]
	v_mfma_f32_16x16x32_bf16 v[110:113], v[144:147], v[214:217], v[110:113]
	v_mfma_f32_16x16x32_bf16 v[98:101], v[148:151], v[198:201], v[98:101]
	v_mfma_f32_16x16x32_bf16 v[98:101], v[152:155], v[214:217], v[98:101]
	v_mfma_f32_16x16x32_bf16 v[94:97], v[134:137], v[218:221], v[94:97]
	v_mfma_f32_16x16x32_bf16 v[94:97], v[144:147], v[222:225], v[94:97]
	v_mfma_f32_16x16x32_bf16 v[82:85], v[148:151], v[218:221], v[82:85]
	v_mfma_f32_16x16x32_bf16 v[82:85], v[152:155], v[222:225], v[82:85]
	v_mfma_f32_16x16x32_bf16 v[78:81], v[134:137], v[226:229], v[78:81]
	v_mfma_f32_16x16x32_bf16 v[78:81], v[144:147], v[230:233], v[78:81]
	v_mfma_f32_16x16x32_bf16 v[66:69], v[148:151], v[226:229], v[66:69]
	v_mfma_f32_16x16x32_bf16 v[66:69], v[152:155], v[230:233], v[66:69]
	s_add_u32 s20, s68, 0xfffc0080
	s_addc_u32 s21, s69, -1
	s_cmp_eq_u32 s97, 12
	s_cselect_b32 s77, s57, s21
	s_cselect_b32 s76, s86, s20
	s_cselect_b32 s21, s51, s96
	s_cselect_b32 s20, s87, s91
	v_mfma_f32_16x16x32_bf16 v[122:125], v[156:159], v[190:193], v[122:125]
	v_mfma_f32_16x16x32_bf16 v[122:125], v[160:163], v[194:197], v[122:125]
	v_mfma_f32_16x16x32_bf16 v[118:121], v[182:185], v[190:193], v[118:121]
	v_mfma_f32_16x16x32_bf16 v[118:121], v[186:189], v[194:197], v[118:121]
	v_mfma_f32_16x16x32_bf16 v[106:109], v[156:159], v[198:201], v[106:109]
	v_mfma_f32_16x16x32_bf16 v[106:109], v[160:163], v[214:217], v[106:109]
	v_mfma_f32_16x16x32_bf16 v[102:105], v[182:185], v[198:201], v[102:105]
	v_mfma_f32_16x16x32_bf16 v[102:105], v[186:189], v[214:217], v[102:105]
	v_mfma_f32_16x16x32_bf16 v[90:93], v[156:159], v[218:221], v[90:93]
	v_mfma_f32_16x16x32_bf16 v[90:93], v[160:163], v[222:225], v[90:93]
	v_mfma_f32_16x16x32_bf16 v[86:89], v[182:185], v[218:221], v[86:89]
	v_mfma_f32_16x16x32_bf16 v[86:89], v[186:189], v[222:225], v[86:89]
	v_mfma_f32_16x16x32_bf16 v[74:77], v[156:159], v[226:229], v[74:77]
	v_mfma_f32_16x16x32_bf16 v[74:77], v[160:163], v[230:233], v[74:77]
	v_mfma_f32_16x16x32_bf16 v[70:73], v[182:185], v[226:229], v[70:73]
	v_mfma_f32_16x16x32_bf16 v[70:73], v[186:189], v[230:233], v[70:73]
	s_barrier
	ds_read_b128 v[190:193], v142 offset:16384
	ds_read_b128 v[194:197], v142 offset:17408
	ds_read_b128 v[198:201], v142 offset:18432
	ds_read_b128 v[214:217], v142 offset:19456
	ds_read_b128 v[218:221], v142 offset:20480
	ds_read_b128 v[222:225], v142 offset:21504
	ds_read_b128 v[226:229], v142 offset:22528
	ds_read_b128 v[230:233], v142 offset:23552
	v_lshl_add_u64 v[202:203], s[20:21], 0, v[0:1]
	s_add_i32 s20, s14, 0x10000
	s_mov_b32 m0, s20
	s_nop 0
	s_nop 0
	global_load_lds_dwordx4 v[202:203], off
	v_lshl_add_u64 v[234:235], v[202:203], 0, s[72:73]
	s_add_i32 m0, s20, 0x2000
	s_add_i32 s20, s14, 0x14000
	global_load_lds_dwordx4 v[234:235], off
	v_lshl_add_u64 v[234:235], v[202:203], 0, s[28:29]
	s_mov_b32 m0, s20
	s_nop 0
	global_load_lds_dwordx4 v[234:235], off
	v_lshl_add_u64 v[234:235], v[202:203], 0, s[82:83]
	s_add_i32 m0, s20, 0x2000
	s_nop 0
	global_load_lds_dwordx4 v[234:235], off
	v_lshl_add_u64 v[234:235], s[76:77], 0, v[130:131]
	s_mov_b32 m0, s43
	v_lshl_add_u64 v[236:237], v[234:235], 0, s[72:73]
	global_load_lds_dwordx4 v[234:235], off
	s_mov_b32 m0, s46
	s_nop 0
	global_load_lds_dwordx4 v[236:237], off
	s_waitcnt vmcnt(8) lgkmcnt(0)
	s_barrier
	v_mfma_f32_16x16x32_bf16 v[62:65], v[134:137], v[190:193], v[62:65]
	v_mfma_f32_16x16x32_bf16 v[62:65], v[144:147], v[194:197], v[62:65]
	v_mfma_f32_16x16x32_bf16 v[50:53], v[148:151], v[190:193], v[50:53]
	v_mfma_f32_16x16x32_bf16 v[50:53], v[152:155], v[194:197], v[50:53]
	v_mfma_f32_16x16x32_bf16 v[46:49], v[134:137], v[198:201], v[46:49]
	v_mfma_f32_16x16x32_bf16 v[46:49], v[144:147], v[214:217], v[46:49]
	v_mfma_f32_16x16x32_bf16 v[34:37], v[148:151], v[198:201], v[34:37]
	v_mfma_f32_16x16x32_bf16 v[34:37], v[152:155], v[214:217], v[34:37]
	v_mfma_f32_16x16x32_bf16 v[30:33], v[134:137], v[218:221], v[30:33]
	v_mfma_f32_16x16x32_bf16 v[30:33], v[144:147], v[222:225], v[30:33]
	v_mfma_f32_16x16x32_bf16 v[18:21], v[148:151], v[218:221], v[18:21]
	v_mfma_f32_16x16x32_bf16 v[18:21], v[152:155], v[222:225], v[18:21]
	v_mfma_f32_16x16x32_bf16 v[14:17], v[134:137], v[226:229], v[14:17]
	v_mfma_f32_16x16x32_bf16 v[14:17], v[144:147], v[230:233], v[14:17]
	v_mfma_f32_16x16x32_bf16 v[6:9], v[148:151], v[226:229], v[6:9]
	v_mfma_f32_16x16x32_bf16 v[6:9], v[152:155], v[230:233], v[6:9]
	v_mfma_f32_16x16x32_bf16 v[58:61], v[156:159], v[190:193], v[58:61]
	v_mfma_f32_16x16x32_bf16 v[58:61], v[160:163], v[194:197], v[58:61]
	v_mfma_f32_16x16x32_bf16 v[54:57], v[182:185], v[190:193], v[54:57]
	v_mfma_f32_16x16x32_bf16 v[54:57], v[186:189], v[194:197], v[54:57]
	v_mfma_f32_16x16x32_bf16 v[42:45], v[156:159], v[198:201], v[42:45]
	v_mfma_f32_16x16x32_bf16 v[42:45], v[160:163], v[214:217], v[42:45]
	v_mfma_f32_16x16x32_bf16 v[38:41], v[182:185], v[198:201], v[38:41]
	v_mfma_f32_16x16x32_bf16 v[38:41], v[186:189], v[214:217], v[38:41]
	v_mfma_f32_16x16x32_bf16 v[26:29], v[156:159], v[218:221], v[26:29]
	v_mfma_f32_16x16x32_bf16 v[26:29], v[160:163], v[222:225], v[26:29]
	v_mfma_f32_16x16x32_bf16 v[22:25], v[182:185], v[218:221], v[22:25]
	v_mfma_f32_16x16x32_bf16 v[22:25], v[186:189], v[222:225], v[22:25]
	v_mfma_f32_16x16x32_bf16 v[10:13], v[156:159], v[226:229], v[10:13]
	v_mfma_f32_16x16x32_bf16 v[10:13], v[160:163], v[230:233], v[10:13]
	v_mfma_f32_16x16x32_bf16 v[2:5], v[182:185], v[226:229], v[2:5]
	v_mfma_f32_16x16x32_bf16 v[2:5], v[186:189], v[230:233], v[2:5]
	s_barrier
	ds_read_b128 v[134:137], v243 offset:32768
	ds_read_b128 v[144:147], v243 offset:33792
	ds_read_b128 v[148:151], v243 offset:34816
	ds_read_b128 v[152:155], v243 offset:35840
	ds_read_b128 v[156:159], v243 offset:49152
	ds_read_b128 v[160:163], v243 offset:50176
	ds_read_b128 v[182:185], v243 offset:51200
	ds_read_b128 v[186:189], v243 offset:52224
	ds_read_b128 v[190:193], v142 offset:32768
	ds_read_b128 v[194:197], v142 offset:33792
	ds_read_b128 v[198:201], v142 offset:34816
	ds_read_b128 v[214:217], v142 offset:35840
	ds_read_b128 v[218:221], v142 offset:36864
	ds_read_b128 v[222:225], v142 offset:37888
	ds_read_b128 v[226:229], v142 offset:38912
	ds_read_b128 v[230:233], v142 offset:39936
	s_mov_b32 m0, s47
	v_lshl_add_u64 v[236:237], v[234:235], 0, s[28:29]
	global_load_lds_dwordx4 v[236:237], off
	v_lshl_add_u64 v[236:237], v[234:235], 0, s[82:83]
	s_mov_b32 m0, s78
	s_nop 0
	global_load_lds_dwordx4 v[236:237], off
	s_waitcnt vmcnt(8) lgkmcnt(0)
	s_barrier
	v_mfma_f32_16x16x32_bf16 v[126:129], v[134:137], v[190:193], v[126:129]
	v_mfma_f32_16x16x32_bf16 v[126:129], v[144:147], v[194:197], v[126:129]
	v_mfma_f32_16x16x32_bf16 v[114:117], v[148:151], v[190:193], v[114:117]
	v_mfma_f32_16x16x32_bf16 v[114:117], v[152:155], v[194:197], v[114:117]
	v_mfma_f32_16x16x32_bf16 v[110:113], v[134:137], v[198:201], v[110:113]
	v_mfma_f32_16x16x32_bf16 v[110:113], v[144:147], v[214:217], v[110:113]
	v_mfma_f32_16x16x32_bf16 v[98:101], v[148:151], v[198:201], v[98:101]
	v_mfma_f32_16x16x32_bf16 v[98:101], v[152:155], v[214:217], v[98:101]
	v_mfma_f32_16x16x32_bf16 v[94:97], v[134:137], v[218:221], v[94:97]
	v_mfma_f32_16x16x32_bf16 v[94:97], v[144:147], v[222:225], v[94:97]
	v_mfma_f32_16x16x32_bf16 v[82:85], v[148:151], v[218:221], v[82:85]
	v_mfma_f32_16x16x32_bf16 v[82:85], v[152:155], v[222:225], v[82:85]
	v_mfma_f32_16x16x32_bf16 v[78:81], v[134:137], v[226:229], v[78:81]
	v_mfma_f32_16x16x32_bf16 v[78:81], v[144:147], v[230:233], v[78:81]
	v_mfma_f32_16x16x32_bf16 v[66:69], v[148:151], v[226:229], v[66:69]
	v_mfma_f32_16x16x32_bf16 v[66:69], v[152:155], v[230:233], v[66:69]
	v_mfma_f32_16x16x32_bf16 v[122:125], v[156:159], v[190:193], v[122:125]
	v_mfma_f32_16x16x32_bf16 v[122:125], v[160:163], v[194:197], v[122:125]
	v_mfma_f32_16x16x32_bf16 v[118:121], v[182:185], v[190:193], v[118:121]
	v_mfma_f32_16x16x32_bf16 v[118:121], v[186:189], v[194:197], v[118:121]
	v_mfma_f32_16x16x32_bf16 v[106:109], v[156:159], v[198:201], v[106:109]
	v_mfma_f32_16x16x32_bf16 v[106:109], v[160:163], v[214:217], v[106:109]
	v_mfma_f32_16x16x32_bf16 v[102:105], v[182:185], v[198:201], v[102:105]
	v_mfma_f32_16x16x32_bf16 v[102:105], v[186:189], v[214:217], v[102:105]
	v_mfma_f32_16x16x32_bf16 v[90:93], v[156:159], v[218:221], v[90:93]
	v_mfma_f32_16x16x32_bf16 v[90:93], v[160:163], v[222:225], v[90:93]
	v_mfma_f32_16x16x32_bf16 v[86:89], v[182:185], v[218:221], v[86:89]
	v_mfma_f32_16x16x32_bf16 v[86:89], v[186:189], v[222:225], v[86:89]
	v_mfma_f32_16x16x32_bf16 v[74:77], v[156:159], v[226:229], v[74:77]
	v_mfma_f32_16x16x32_bf16 v[74:77], v[160:163], v[230:233], v[74:77]
	v_mfma_f32_16x16x32_bf16 v[70:73], v[182:185], v[226:229], v[70:73]
	v_mfma_f32_16x16x32_bf16 v[70:73], v[186:189], v[230:233], v[70:73]
	s_barrier
	ds_read_b128 v[190:193], v142 offset:49152
	ds_read_b128 v[194:197], v142 offset:50176
	ds_read_b128 v[198:201], v142 offset:51200
	ds_read_b128 v[214:217], v142 offset:52224
	ds_read_b128 v[218:221], v142 offset:53248
	ds_read_b128 v[222:225], v142 offset:54272
	ds_read_b128 v[226:229], v142 offset:55296
	ds_read_b128 v[230:233], v142 offset:56320
	s_add_i32 s20, s14, 0x18000
	s_mov_b32 m0, s20
	v_lshl_add_u64 v[236:237], v[202:203], 0, s[34:35]
	global_load_lds_dwordx4 v[236:237], off
	v_lshl_add_u64 v[236:237], v[202:203], 0, s[38:39]
	s_add_i32 m0, s20, 0x2000
	s_add_i32 s20, s14, 0x1c000
	global_load_lds_dwordx4 v[236:237], off
	v_lshl_add_u64 v[236:237], v[202:203], 0, s[44:45]
	s_mov_b32 m0, s20
	v_lshl_add_u64 v[202:203], v[202:203], 0, s[10:11]
	global_load_lds_dwordx4 v[236:237], off
	s_add_i32 m0, s20, 0x2000
	s_nop 0
	global_load_lds_dwordx4 v[202:203], off
	v_lshl_add_u64 v[202:203], v[234:235], 0, s[34:35]
	s_mov_b32 m0, s79
	s_nop 0
	global_load_lds_dwordx4 v[202:203], off
	v_lshl_add_u64 v[202:203], v[234:235], 0, s[38:39]
	s_mov_b32 m0, s88
	s_nop 0
	global_load_lds_dwordx4 v[202:203], off
	s_waitcnt vmcnt(8) lgkmcnt(0)
	s_barrier
	v_mfma_f32_16x16x32_bf16 v[62:65], v[134:137], v[190:193], v[62:65]
	v_mfma_f32_16x16x32_bf16 v[62:65], v[144:147], v[194:197], v[62:65]
	v_mfma_f32_16x16x32_bf16 v[50:53], v[148:151], v[190:193], v[50:53]
	v_mfma_f32_16x16x32_bf16 v[50:53], v[152:155], v[194:197], v[50:53]
	v_mfma_f32_16x16x32_bf16 v[46:49], v[134:137], v[198:201], v[46:49]
	v_mfma_f32_16x16x32_bf16 v[46:49], v[144:147], v[214:217], v[46:49]
	v_mfma_f32_16x16x32_bf16 v[34:37], v[148:151], v[198:201], v[34:37]
	v_mfma_f32_16x16x32_bf16 v[34:37], v[152:155], v[214:217], v[34:37]
	v_mfma_f32_16x16x32_bf16 v[30:33], v[134:137], v[218:221], v[30:33]
	v_mfma_f32_16x16x32_bf16 v[30:33], v[144:147], v[222:225], v[30:33]
	v_mfma_f32_16x16x32_bf16 v[18:21], v[148:151], v[218:221], v[18:21]
	v_mfma_f32_16x16x32_bf16 v[18:21], v[152:155], v[222:225], v[18:21]
	v_mfma_f32_16x16x32_bf16 v[14:17], v[134:137], v[226:229], v[14:17]
	v_mfma_f32_16x16x32_bf16 v[14:17], v[144:147], v[230:233], v[14:17]
	v_mfma_f32_16x16x32_bf16 v[6:9], v[148:151], v[226:229], v[6:9]
	v_mfma_f32_16x16x32_bf16 v[6:9], v[152:155], v[230:233], v[6:9]
	s_add_i32 s97, s97, 2
	s_add_u32 s68, s68, 0x100
	s_addc_u32 s69, s69, 0
	s_add_u32 s91, s91, 0x100
	s_addc_u32 s96, s96, 0
	v_mfma_f32_16x16x32_bf16 v[58:61], v[156:159], v[190:193], v[58:61]
	v_mfma_f32_16x16x32_bf16 v[58:61], v[160:163], v[194:197], v[58:61]
	v_mfma_f32_16x16x32_bf16 v[54:57], v[182:185], v[190:193], v[54:57]
	v_mfma_f32_16x16x32_bf16 v[54:57], v[186:189], v[194:197], v[54:57]
	v_mfma_f32_16x16x32_bf16 v[42:45], v[156:159], v[198:201], v[42:45]
	v_mfma_f32_16x16x32_bf16 v[42:45], v[160:163], v[214:217], v[42:45]
	v_mfma_f32_16x16x32_bf16 v[38:41], v[182:185], v[198:201], v[38:41]
	v_mfma_f32_16x16x32_bf16 v[38:41], v[186:189], v[214:217], v[38:41]
	v_mfma_f32_16x16x32_bf16 v[26:29], v[156:159], v[218:221], v[26:29]
	v_mfma_f32_16x16x32_bf16 v[26:29], v[160:163], v[222:225], v[26:29]
	v_mfma_f32_16x16x32_bf16 v[22:25], v[182:185], v[218:221], v[22:25]
	v_mfma_f32_16x16x32_bf16 v[22:25], v[186:189], v[222:225], v[22:25]
	v_mfma_f32_16x16x32_bf16 v[10:13], v[156:159], v[226:229], v[10:13]
	v_mfma_f32_16x16x32_bf16 v[10:13], v[160:163], v[230:233], v[10:13]
	v_mfma_f32_16x16x32_bf16 v[2:5], v[182:185], v[226:229], v[2:5]
	v_mfma_f32_16x16x32_bf16 v[2:5], v[186:189], v[230:233], v[2:5]
	s_barrier
	s_cmp_gt_u32 s97, 13
	s_cbranch_scc0 .LBB0_488
	s_setprio 0
	s_and_b64 vcc, exec, s[48:49]
	s_cbranch_vccz .LBB0_491
	s_barrier

.Lmid1_604:
	s_add_i32 m0, s89, 0xc000
	v_lshl_add_u64 v[162:163], s[6:7], 0, v[132:133]
	global_load_lds_dwordx4 v[162:163], off
	v_lshl_add_u64 v[162:163], v[162:163], 0, s[64:65]
	s_add_i32 m0, s89, 0xe000
	s_nop 0
	global_load_lds_dwordx4 v[162:163], off
	s_waitcnt vmcnt(8) lgkmcnt(0)
	s_barrier
	v_mfma_f32_16x16x32_bf16 v[126:129], v[134:137], v[190:193], 0
	v_mfma_f32_16x16x32_bf16 v[126:129], v[142:145], v[194:197], v[126:129]
	v_mfma_f32_16x16x32_bf16 v[122:125], v[146:149], v[190:193], 0
	v_mfma_f32_16x16x32_bf16 v[122:125], v[150:153], v[194:197], v[122:125]
	v_mfma_f32_16x16x32_bf16 v[110:113], v[134:137], v[198:201], 0
	v_mfma_f32_16x16x32_bf16 v[110:113], v[142:145], v[214:217], v[110:113]
	v_mfma_f32_16x16x32_bf16 v[106:109], v[146:149], v[198:201], 0
	v_mfma_f32_16x16x32_bf16 v[106:109], v[150:153], v[214:217], v[106:109]
	v_mfma_f32_16x16x32_bf16 v[94:97], v[134:137], v[218:221], 0
	v_mfma_f32_16x16x32_bf16 v[94:97], v[142:145], v[222:225], v[94:97]
	v_mfma_f32_16x16x32_bf16 v[90:93], v[146:149], v[218:221], 0
	v_mfma_f32_16x16x32_bf16 v[90:93], v[150:153], v[222:225], v[90:93]
	v_mfma_f32_16x16x32_bf16 v[78:81], v[134:137], v[226:229], 0
	v_mfma_f32_16x16x32_bf16 v[78:81], v[142:145], v[230:233], v[78:81]
	v_mfma_f32_16x16x32_bf16 v[74:77], v[146:149], v[226:229], 0
	v_mfma_f32_16x16x32_bf16 v[74:77], v[150:153], v[230:233], v[74:77]
	s_add_u32 s20, s6, 0xfffe0080
	s_addc_u32 s21, s7, -1
	s_cmp_eq_u32 s84, 4
	s_cselect_b32 s69, s42, s21
	s_cselect_b32 s68, s43, s20
	s_cselect_b32 s21, s46, s51
	s_cselect_b32 s20, s47, s49
	v_mfma_f32_16x16x32_bf16 v[118:121], v[154:157], v[190:193], 0
	v_mfma_f32_16x16x32_bf16 v[118:121], v[158:161], v[194:197], v[118:121]
	v_mfma_f32_16x16x32_bf16 v[114:117], v[182:185], v[190:193], 0
	v_mfma_f32_16x16x32_bf16 v[114:117], v[186:189], v[194:197], v[114:117]
	v_mfma_f32_16x16x32_bf16 v[102:105], v[154:157], v[198:201], 0
	v_mfma_f32_16x16x32_bf16 v[102:105], v[158:161], v[214:217], v[102:105]
	v_mfma_f32_16x16x32_bf16 v[98:101], v[182:185], v[198:201], 0
	v_mfma_f32_16x16x32_bf16 v[98:101], v[186:189], v[214:217], v[98:101]
	v_mfma_f32_16x16x32_bf16 v[86:89], v[154:157], v[218:221], 0
	v_mfma_f32_16x16x32_bf16 v[86:89], v[158:161], v[222:225], v[86:89]
	v_mfma_f32_16x16x32_bf16 v[82:85], v[182:185], v[218:221], 0
	v_mfma_f32_16x16x32_bf16 v[82:85], v[186:189], v[222:225], v[82:85]
	v_mfma_f32_16x16x32_bf16 v[70:73], v[154:157], v[226:229], 0
	v_mfma_f32_16x16x32_bf16 v[70:73], v[158:161], v[230:233], v[70:73]
	v_mfma_f32_16x16x32_bf16 v[66:69], v[182:185], v[226:229], 0
	v_mfma_f32_16x16x32_bf16 v[66:69], v[186:189], v[230:233], v[66:69]
	s_barrier
	ds_read_b128 v[190:193], v141 offset:16384
	ds_read_b128 v[194:197], v141 offset:17408
	ds_read_b128 v[198:201], v141 offset:18432
	ds_read_b128 v[214:217], v141 offset:19456
	ds_read_b128 v[218:221], v141 offset:20480
	ds_read_b128 v[222:225], v141 offset:21504
	ds_read_b128 v[226:229], v141 offset:22528
	ds_read_b128 v[230:233], v141 offset:23552
	v_lshl_add_u64 v[162:163], s[20:21], 0, v[0:1]
	s_add_i32 s20, s88, 0x10000
	s_mov_b32 m0, s20
	s_nop 0
	s_nop 0
	global_load_lds_dwordx4 v[162:163], off
	v_lshl_add_u64 v[202:203], v[162:163], 0, s[64:65]
	s_add_i32 m0, s20, 0x2000
	s_add_i32 s20, s88, 0x14000
	global_load_lds_dwordx4 v[202:203], off
	v_lshl_add_u64 v[202:203], v[162:163], 0, s[72:73]
	s_mov_b32 m0, s20
	s_nop 0
	global_load_lds_dwordx4 v[202:203], off
	v_lshl_add_u64 v[202:203], v[162:163], 0, s[74:75]
	s_add_i32 m0, s20, 0x2000
	s_nop 0
	global_load_lds_dwordx4 v[202:203], off
	v_lshl_add_u64 v[202:203], s[68:69], 0, v[130:131]
	s_mov_b32 m0, s89
	v_lshl_add_u64 v[234:235], v[202:203], 0, s[64:65]
	global_load_lds_dwordx4 v[202:203], off
	s_mov_b32 m0, s90
	s_nop 0
	global_load_lds_dwordx4 v[234:235], off
	s_waitcnt vmcnt(8) lgkmcnt(0)
	s_barrier
	v_mfma_f32_16x16x32_bf16 v[62:65], v[134:137], v[190:193], 0
	v_mfma_f32_16x16x32_bf16 v[62:65], v[142:145], v[194:197], v[62:65]
	v_mfma_f32_16x16x32_bf16 v[58:61], v[146:149], v[190:193], 0
	v_mfma_f32_16x16x32_bf16 v[58:61], v[150:153], v[194:197], v[58:61]
	v_mfma_f32_16x16x32_bf16 v[46:49], v[134:137], v[198:201], 0
	v_mfma_f32_16x16x32_bf16 v[46:49], v[142:145], v[214:217], v[46:49]
	v_mfma_f32_16x16x32_bf16 v[42:45], v[146:149], v[198:201], 0
	v_mfma_f32_16x16x32_bf16 v[42:45], v[150:153], v[214:217], v[42:45]
	v_mfma_f32_16x16x32_bf16 v[30:33], v[134:137], v[218:221], 0
	v_mfma_f32_16x16x32_bf16 v[30:33], v[142:145], v[222:225], v[30:33]
	v_mfma_f32_16x16x32_bf16 v[26:29], v[146:149], v[218:221], 0
	v_mfma_f32_16x16x32_bf16 v[26:29], v[150:153], v[222:225], v[26:29]
	v_mfma_f32_16x16x32_bf16 v[14:17], v[134:137], v[226:229], 0
	v_mfma_f32_16x16x32_bf16 v[14:17], v[142:145], v[230:233], v[14:17]
	v_mfma_f32_16x16x32_bf16 v[10:13], v[146:149], v[226:229], 0
	v_mfma_f32_16x16x32_bf16 v[10:13], v[150:153], v[230:233], v[10:13]
	v_mfma_f32_16x16x32_bf16 v[54:57], v[154:157], v[190:193], 0
	v_mfma_f32_16x16x32_bf16 v[54:57], v[158:161], v[194:197], v[54:57]
	v_mfma_f32_16x16x32_bf16 v[50:53], v[182:185], v[190:193], 0
	v_mfma_f32_16x16x32_bf16 v[50:53], v[186:189], v[194:197], v[50:53]
	v_mfma_f32_16x16x32_bf16 v[38:41], v[154:157], v[198:201], 0
	v_mfma_f32_16x16x32_bf16 v[38:41], v[158:161], v[214:217], v[38:41]
	v_mfma_f32_16x16x32_bf16 v[34:37], v[182:185], v[198:201], 0
	v_mfma_f32_16x16x32_bf16 v[34:37], v[186:189], v[214:217], v[34:37]
	v_mfma_f32_16x16x32_bf16 v[22:25], v[154:157], v[218:221], 0
	v_mfma_f32_16x16x32_bf16 v[22:25], v[158:161], v[222:225], v[22:25]
	v_mfma_f32_16x16x32_bf16 v[18:21], v[182:185], v[218:221], 0
	v_mfma_f32_16x16x32_bf16 v[18:21], v[186:189], v[222:225], v[18:21]
	v_mfma_f32_16x16x32_bf16 v[6:9], v[154:157], v[226:229], 0
	v_mfma_f32_16x16x32_bf16 v[6:9], v[158:161], v[230:233], v[6:9]
	v_mfma_f32_16x16x32_bf16 v[2:5], v[182:185], v[226:229], 0
	v_mfma_f32_16x16x32_bf16 v[2:5], v[186:189], v[230:233], v[2:5]
	s_barrier
	ds_read_b128 v[134:137], v243 offset:32768
	ds_read_b128 v[142:145], v243 offset:33792
	ds_read_b128 v[146:149], v243 offset:34816
	ds_read_b128 v[150:153], v243 offset:35840
	ds_read_b128 v[154:157], v243 offset:49152
	ds_read_b128 v[158:161], v243 offset:50176
	ds_read_b128 v[182:185], v243 offset:51200
	ds_read_b128 v[186:189], v243 offset:52224
	ds_read_b128 v[190:193], v141 offset:32768
	ds_read_b128 v[194:197], v141 offset:33792
	ds_read_b128 v[198:201], v141 offset:34816
	ds_read_b128 v[214:217], v141 offset:35840
	ds_read_b128 v[218:221], v141 offset:36864
	ds_read_b128 v[222:225], v141 offset:37888
	ds_read_b128 v[226:229], v141 offset:38912
	ds_read_b128 v[230:233], v141 offset:39936
	s_mov_b32 m0, s91
	v_lshl_add_u64 v[234:235], v[202:203], 0, s[72:73]
	global_load_lds_dwordx4 v[234:235], off
	v_lshl_add_u64 v[234:235], v[202:203], 0, s[74:75]
	s_mov_b32 m0, s96
	s_nop 0
	global_load_lds_dwordx4 v[234:235], off
	s_waitcnt vmcnt(8) lgkmcnt(0)
	s_barrier
	v_mfma_f32_16x16x32_bf16 v[126:129], v[134:137], v[190:193], v[126:129]
	v_mfma_f32_16x16x32_bf16 v[126:129], v[142:145], v[194:197], v[126:129]
	v_mfma_f32_16x16x32_bf16 v[122:125], v[146:149], v[190:193], v[122:125]
	v_mfma_f32_16x16x32_bf16 v[122:125], v[150:153], v[194:197], v[122:125]
	v_mfma_f32_16x16x32_bf16 v[110:113], v[134:137], v[198:201], v[110:113]
	v_mfma_f32_16x16x32_bf16 v[110:113], v[142:145], v[214:217], v[110:113]
	v_mfma_f32_16x16x32_bf16 v[106:109], v[146:149], v[198:201], v[106:109]
	v_mfma_f32_16x16x32_bf16 v[106:109], v[150:153], v[214:217], v[106:109]
	v_mfma_f32_16x16x32_bf16 v[94:97], v[134:137], v[218:221], v[94:97]
	v_mfma_f32_16x16x32_bf16 v[94:97], v[142:145], v[222:225], v[94:97]
	v_mfma_f32_16x16x32_bf16 v[90:93], v[146:149], v[218:221], v[90:93]
	v_mfma_f32_16x16x32_bf16 v[90:93], v[150:153], v[222:225], v[90:93]
	v_mfma_f32_16x16x32_bf16 v[78:81], v[134:137], v[226:229], v[78:81]
	v_mfma_f32_16x16x32_bf16 v[78:81], v[142:145], v[230:233], v[78:81]
	v_mfma_f32_16x16x32_bf16 v[74:77], v[146:149], v[226:229], v[74:77]
	v_mfma_f32_16x16x32_bf16 v[74:77], v[150:153], v[230:233], v[74:77]
	v_mfma_f32_16x16x32_bf16 v[118:121], v[154:157], v[190:193], v[118:121]
	v_mfma_f32_16x16x32_bf16 v[118:121], v[158:161], v[194:197], v[118:121]
	v_mfma_f32_16x16x32_bf16 v[114:117], v[182:185], v[190:193], v[114:117]
	v_mfma_f32_16x16x32_bf16 v[114:117], v[186:189], v[194:197], v[114:117]
	v_mfma_f32_16x16x32_bf16 v[102:105], v[154:157], v[198:201], v[102:105]
	v_mfma_f32_16x16x32_bf16 v[102:105], v[158:161], v[214:217], v[102:105]
	v_mfma_f32_16x16x32_bf16 v[98:101], v[182:185], v[198:201], v[98:101]
	v_mfma_f32_16x16x32_bf16 v[98:101], v[186:189], v[214:217], v[98:101]
	v_mfma_f32_16x16x32_bf16 v[86:89], v[154:157], v[218:221], v[86:89]
	v_mfma_f32_16x16x32_bf16 v[86:89], v[158:161], v[222:225], v[86:89]
	v_mfma_f32_16x16x32_bf16 v[82:85], v[182:185], v[218:221], v[82:85]
	v_mfma_f32_16x16x32_bf16 v[82:85], v[186:189], v[222:225], v[82:85]
	v_mfma_f32_16x16x32_bf16 v[70:73], v[154:157], v[226:229], v[70:73]
	v_mfma_f32_16x16x32_bf16 v[70:73], v[158:161], v[230:233], v[70:73]
	v_mfma_f32_16x16x32_bf16 v[66:69], v[182:185], v[226:229], v[66:69]
	v_mfma_f32_16x16x32_bf16 v[66:69], v[186:189], v[230:233], v[66:69]
	s_barrier
	ds_read_b128 v[190:193], v141 offset:49152
	ds_read_b128 v[194:197], v141 offset:50176
	ds_read_b128 v[198:201], v141 offset:51200
	ds_read_b128 v[214:217], v141 offset:52224
	ds_read_b128 v[218:221], v141 offset:53248
	ds_read_b128 v[222:225], v141 offset:54272
	ds_read_b128 v[226:229], v141 offset:55296
	ds_read_b128 v[230:233], v141 offset:56320
	s_add_i32 s20, s88, 0x18000
	s_mov_b32 m0, s20
	v_lshl_add_u64 v[234:235], v[162:163], 0, s[34:35]
	global_load_lds_dwordx4 v[234:235], off
	v_lshl_add_u64 v[234:235], v[162:163], 0, s[80:81]
	s_add_i32 m0, s20, 0x2000
	s_add_i32 s20, s88, 0x1c000
	global_load_lds_dwordx4 v[234:235], off
	v_lshl_add_u64 v[234:235], v[162:163], 0, s[38:39]
	s_mov_b32 m0, s20
	v_lshl_add_u64 v[162:163], v[162:163], 0, s[86:87]
	global_load_lds_dwordx4 v[234:235], off
	s_add_i32 m0, s20, 0x2000
	s_nop 0
	global_load_lds_dwordx4 v[162:163], off
	v_lshl_add_u64 v[162:163], v[202:203], 0, s[34:35]
	s_mov_b32 m0, s97
	s_nop 0
	global_load_lds_dwordx4 v[162:163], off
	v_lshl_add_u64 v[162:163], v[202:203], 0, s[80:81]
	s_mov_b32 m0, s58
	s_nop 0
	global_load_lds_dwordx4 v[162:163], off
	s_waitcnt vmcnt(8) lgkmcnt(0)
	s_barrier
	v_mfma_f32_16x16x32_bf16 v[62:65], v[134:137], v[190:193], v[62:65]
	v_mfma_f32_16x16x32_bf16 v[62:65], v[142:145], v[194:197], v[62:65]
	v_mfma_f32_16x16x32_bf16 v[58:61], v[146:149], v[190:193], v[58:61]
	v_mfma_f32_16x16x32_bf16 v[58:61], v[150:153], v[194:197], v[58:61]
	v_mfma_f32_16x16x32_bf16 v[46:49], v[134:137], v[198:201], v[46:49]
	v_mfma_f32_16x16x32_bf16 v[46:49], v[142:145], v[214:217], v[46:49]
	v_mfma_f32_16x16x32_bf16 v[42:45], v[146:149], v[198:201], v[42:45]
	v_mfma_f32_16x16x32_bf16 v[42:45], v[150:153], v[214:217], v[42:45]
	v_mfma_f32_16x16x32_bf16 v[30:33], v[134:137], v[218:221], v[30:33]
	v_mfma_f32_16x16x32_bf16 v[30:33], v[142:145], v[222:225], v[30:33]
	v_mfma_f32_16x16x32_bf16 v[26:29], v[146:149], v[218:221], v[26:29]
	v_mfma_f32_16x16x32_bf16 v[26:29], v[150:153], v[222:225], v[26:29]
	v_mfma_f32_16x16x32_bf16 v[14:17], v[134:137], v[226:229], v[14:17]
	v_mfma_f32_16x16x32_bf16 v[14:17], v[142:145], v[230:233], v[14:17]
	v_mfma_f32_16x16x32_bf16 v[10:13], v[146:149], v[226:229], v[10:13]
	v_mfma_f32_16x16x32_bf16 v[10:13], v[150:153], v[230:233], v[10:13]
	s_add_i32 s84, s84, 2
	s_add_u32 s6, s6, 0x100
	s_addc_u32 s7, s7, 0
	s_add_u32 s49, s49, 0x100
	s_addc_u32 s51, s51, 0
	v_mfma_f32_16x16x32_bf16 v[54:57], v[154:157], v[190:193], v[54:57]
	v_mfma_f32_16x16x32_bf16 v[54:57], v[158:161], v[194:197], v[54:57]
	v_mfma_f32_16x16x32_bf16 v[50:53], v[182:185], v[190:193], v[50:53]
	v_mfma_f32_16x16x32_bf16 v[50:53], v[186:189], v[194:197], v[50:53]
	v_mfma_f32_16x16x32_bf16 v[38:41], v[154:157], v[198:201], v[38:41]
	v_mfma_f32_16x16x32_bf16 v[38:41], v[158:161], v[214:217], v[38:41]
	v_mfma_f32_16x16x32_bf16 v[34:37], v[182:185], v[198:201], v[34:37]
	v_mfma_f32_16x16x32_bf16 v[34:37], v[186:189], v[214:217], v[34:37]
	v_mfma_f32_16x16x32_bf16 v[22:25], v[154:157], v[218:221], v[22:25]
	v_mfma_f32_16x16x32_bf16 v[22:25], v[158:161], v[222:225], v[22:25]
	v_mfma_f32_16x16x32_bf16 v[18:21], v[182:185], v[218:221], v[18:21]
	v_mfma_f32_16x16x32_bf16 v[18:21], v[186:189], v[222:225], v[18:21]
	v_mfma_f32_16x16x32_bf16 v[6:9], v[154:157], v[226:229], v[6:9]
	v_mfma_f32_16x16x32_bf16 v[6:9], v[158:161], v[230:233], v[6:9]
	v_mfma_f32_16x16x32_bf16 v[2:5], v[182:185], v[226:229], v[2:5]
	v_mfma_f32_16x16x32_bf16 v[2:5], v[186:189], v[230:233], v[2:5]
	s_barrier
	s_branch .LBB0_604
	.p2alignl 6, 3212836864
.LBB0_604:
	ds_read_b128 v[134:137], v243
	ds_read_b128 v[142:145], v243 offset:1024
	ds_read_b128 v[146:149], v243 offset:2048
	ds_read_b128 v[150:153], v243 offset:3072
	ds_read_b128 v[154:157], v243 offset:16384
	ds_read_b128 v[158:161], v243 offset:17408
	ds_read_b128 v[182:185], v243 offset:18432
	ds_read_b128 v[186:189], v243 offset:19456
	ds_read_b128 v[190:193], v141
	ds_read_b128 v[194:197], v141 offset:1024
	ds_read_b128 v[198:201], v141 offset:2048
	ds_read_b128 v[214:217], v141 offset:3072
	ds_read_b128 v[218:221], v141 offset:4096
	ds_read_b128 v[222:225], v141 offset:5120
	ds_read_b128 v[226:229], v141 offset:6144
	ds_read_b128 v[230:233], v141 offset:7168
	s_add_i32 m0, s89, 0xc000
	v_lshl_add_u64 v[162:163], s[6:7], 0, v[132:133]
	global_load_lds_dwordx4 v[162:163], off
	v_lshl_add_u64 v[162:163], v[162:163], 0, s[64:65]
	s_add_i32 m0, s89, 0xe000
	s_nop 0
	global_load_lds_dwordx4 v[162:163], off
	s_waitcnt vmcnt(8) lgkmcnt(0)
	s_barrier
	v_mfma_f32_16x16x32_bf16 v[126:129], v[134:137], v[190:193], v[126:129]
	v_mfma_f32_16x16x32_bf16 v[126:129], v[142:145], v[194:197], v[126:129]
	v_mfma_f32_16x16x32_bf16 v[122:125], v[146:149], v[190:193], v[122:125]
	v_mfma_f32_16x16x32_bf16 v[122:125], v[150:153], v[194:197], v[122:125]
	v_mfma_f32_16x16x32_bf16 v[110:113], v[134:137], v[198:201], v[110:113]
	v_mfma_f32_16x16x32_bf16 v[110:113], v[142:145], v[214:217], v[110:113]
	v_mfma_f32_16x16x32_bf16 v[106:109], v[146:149], v[198:201], v[106:109]
	v_mfma_f32_16x16x32_bf16 v[106:109], v[150:153], v[214:217], v[106:109]
	v_mfma_f32_16x16x32_bf16 v[94:97], v[134:137], v[218:221], v[94:97]
	v_mfma_f32_16x16x32_bf16 v[94:97], v[142:145], v[222:225], v[94:97]
	v_mfma_f32_16x16x32_bf16 v[90:93], v[146:149], v[218:221], v[90:93]
	v_mfma_f32_16x16x32_bf16 v[90:93], v[150:153], v[222:225], v[90:93]
	v_mfma_f32_16x16x32_bf16 v[78:81], v[134:137], v[226:229], v[78:81]
	v_mfma_f32_16x16x32_bf16 v[78:81], v[142:145], v[230:233], v[78:81]
	v_mfma_f32_16x16x32_bf16 v[74:77], v[146:149], v[226:229], v[74:77]
	v_mfma_f32_16x16x32_bf16 v[74:77], v[150:153], v[230:233], v[74:77]
	s_add_u32 s20, s6, 0xfffe0080
	s_addc_u32 s21, s7, -1
	s_cmp_eq_u32 s84, 4
	s_cselect_b32 s69, s42, s21
	s_cselect_b32 s68, s43, s20
	s_cselect_b32 s21, s46, s51
	s_cselect_b32 s20, s47, s49
	v_mfma_f32_16x16x32_bf16 v[118:121], v[154:157], v[190:193], v[118:121]
	v_mfma_f32_16x16x32_bf16 v[118:121], v[158:161], v[194:197], v[118:121]
	v_mfma_f32_16x16x32_bf16 v[114:117], v[182:185], v[190:193], v[114:117]
	v_mfma_f32_16x16x32_bf16 v[114:117], v[186:189], v[194:197], v[114:117]
	v_mfma_f32_16x16x32_bf16 v[102:105], v[154:157], v[198:201], v[102:105]
	v_mfma_f32_16x16x32_bf16 v[102:105], v[158:161], v[214:217], v[102:105]
	v_mfma_f32_16x16x32_bf16 v[98:101], v[182:185], v[198:201], v[98:101]
	v_mfma_f32_16x16x32_bf16 v[98:101], v[186:189], v[214:217], v[98:101]
	v_mfma_f32_16x16x32_bf16 v[86:89], v[154:157], v[218:221], v[86:89]
	v_mfma_f32_16x16x32_bf16 v[86:89], v[158:161], v[222:225], v[86:89]
	v_mfma_f32_16x16x32_bf16 v[82:85], v[182:185], v[218:221], v[82:85]
	v_mfma_f32_16x16x32_bf16 v[82:85], v[186:189], v[222:225], v[82:85]
	v_mfma_f32_16x16x32_bf16 v[70:73], v[154:157], v[226:229], v[70:73]
	v_mfma_f32_16x16x32_bf16 v[70:73], v[158:161], v[230:233], v[70:73]
	v_mfma_f32_16x16x32_bf16 v[66:69], v[182:185], v[226:229], v[66:69]
	v_mfma_f32_16x16x32_bf16 v[66:69], v[186:189], v[230:233], v[66:69]
	s_barrier
	ds_read_b128 v[190:193], v141 offset:16384
	ds_read_b128 v[194:197], v141 offset:17408
	ds_read_b128 v[198:201], v141 offset:18432
	ds_read_b128 v[214:217], v141 offset:19456
	ds_read_b128 v[218:221], v141 offset:20480
	ds_read_b128 v[222:225], v141 offset:21504
	ds_read_b128 v[226:229], v141 offset:22528
	ds_read_b128 v[230:233], v141 offset:23552
	v_lshl_add_u64 v[162:163], s[20:21], 0, v[0:1]
	s_add_i32 s20, s88, 0x10000
	s_mov_b32 m0, s20
	s_nop 0
	s_nop 0
	global_load_lds_dwordx4 v[162:163], off
	v_lshl_add_u64 v[202:203], v[162:163], 0, s[64:65]
	s_add_i32 m0, s20, 0x2000
	s_add_i32 s20, s88, 0x14000
	global_load_lds_dwordx4 v[202:203], off
	v_lshl_add_u64 v[202:203], v[162:163], 0, s[72:73]
	s_mov_b32 m0, s20
	s_nop 0
	global_load_lds_dwordx4 v[202:203], off
	v_lshl_add_u64 v[202:203], v[162:163], 0, s[74:75]
	s_add_i32 m0, s20, 0x2000
	s_nop 0
	global_load_lds_dwordx4 v[202:203], off
	v_lshl_add_u64 v[202:203], s[68:69], 0, v[130:131]
	s_mov_b32 m0, s89
	v_lshl_add_u64 v[234:235], v[202:203], 0, s[64:65]
	global_load_lds_dwordx4 v[202:203], off
	s_mov_b32 m0, s90
	s_nop 0
	global_load_lds_dwordx4 v[234:235], off
	s_waitcnt vmcnt(8) lgkmcnt(0)
	s_barrier
	v_mfma_f32_16x16x32_bf16 v[62:65], v[134:137], v[190:193], v[62:65]
	v_mfma_f32_16x16x32_bf16 v[62:65], v[142:145], v[194:197], v[62:65]
	v_mfma_f32_16x16x32_bf16 v[58:61], v[146:149], v[190:193], v[58:61]
	v_mfma_f32_16x16x32_bf16 v[58:61], v[150:153], v[194:197], v[58:61]
	v_mfma_f32_16x16x32_bf16 v[46:49], v[134:137], v[198:201], v[46:49]
	v_mfma_f32_16x16x32_bf16 v[46:49], v[142:145], v[214:217], v[46:49]
	v_mfma_f32_16x16x32_bf16 v[42:45], v[146:149], v[198:201], v[42:45]
	v_mfma_f32_16x16x32_bf16 v[42:45], v[150:153], v[214:217], v[42:45]
	v_mfma_f32_16x16x32_bf16 v[30:33], v[134:137], v[218:221], v[30:33]
	v_mfma_f32_16x16x32_bf16 v[30:33], v[142:145], v[222:225], v[30:33]
	v_mfma_f32_16x16x32_bf16 v[26:29], v[146:149], v[218:221], v[26:29]
	v_mfma_f32_16x16x32_bf16 v[26:29], v[150:153], v[222:225], v[26:29]
	v_mfma_f32_16x16x32_bf16 v[14:17], v[134:137], v[226:229], v[14:17]
	v_mfma_f32_16x16x32_bf16 v[14:17], v[142:145], v[230:233], v[14:17]
	v_mfma_f32_16x16x32_bf16 v[10:13], v[146:149], v[226:229], v[10:13]
	v_mfma_f32_16x16x32_bf16 v[10:13], v[150:153], v[230:233], v[10:13]
	v_mfma_f32_16x16x32_bf16 v[54:57], v[154:157], v[190:193], v[54:57]
	v_mfma_f32_16x16x32_bf16 v[54:57], v[158:161], v[194:197], v[54:57]
	v_mfma_f32_16x16x32_bf16 v[50:53], v[182:185], v[190:193], v[50:53]
	v_mfma_f32_16x16x32_bf16 v[50:53], v[186:189], v[194:197], v[50:53]
	v_mfma_f32_16x16x32_bf16 v[38:41], v[154:157], v[198:201], v[38:41]
	v_mfma_f32_16x16x32_bf16 v[38:41], v[158:161], v[214:217], v[38:41]
	v_mfma_f32_16x16x32_bf16 v[34:37], v[182:185], v[198:201], v[34:37]
	v_mfma_f32_16x16x32_bf16 v[34:37], v[186:189], v[214:217], v[34:37]
	v_mfma_f32_16x16x32_bf16 v[22:25], v[154:157], v[218:221], v[22:25]
	v_mfma_f32_16x16x32_bf16 v[22:25], v[158:161], v[222:225], v[22:25]
	v_mfma_f32_16x16x32_bf16 v[18:21], v[182:185], v[218:221], v[18:21]
	v_mfma_f32_16x16x32_bf16 v[18:21], v[186:189], v[222:225], v[18:21]
	v_mfma_f32_16x16x32_bf16 v[6:9], v[154:157], v[226:229], v[6:9]
	v_mfma_f32_16x16x32_bf16 v[6:9], v[158:161], v[230:233], v[6:9]
	v_mfma_f32_16x16x32_bf16 v[2:5], v[182:185], v[226:229], v[2:5]
	v_mfma_f32_16x16x32_bf16 v[2:5], v[186:189], v[230:233], v[2:5]
	s_barrier
	ds_read_b128 v[134:137], v243 offset:32768
	ds_read_b128 v[142:145], v243 offset:33792
	ds_read_b128 v[146:149], v243 offset:34816
	ds_read_b128 v[150:153], v243 offset:35840
	ds_read_b128 v[154:157], v243 offset:49152
	ds_read_b128 v[158:161], v243 offset:50176
	ds_read_b128 v[182:185], v243 offset:51200
	ds_read_b128 v[186:189], v243 offset:52224
	ds_read_b128 v[190:193], v141 offset:32768
	ds_read_b128 v[194:197], v141 offset:33792
	ds_read_b128 v[198:201], v141 offset:34816
	ds_read_b128 v[214:217], v141 offset:35840
	ds_read_b128 v[218:221], v141 offset:36864
	ds_read_b128 v[222:225], v141 offset:37888
	ds_read_b128 v[226:229], v141 offset:38912
	ds_read_b128 v[230:233], v141 offset:39936
	s_mov_b32 m0, s91
	v_lshl_add_u64 v[234:235], v[202:203], 0, s[72:73]
	global_load_lds_dwordx4 v[234:235], off
	v_lshl_add_u64 v[234:235], v[202:203], 0, s[74:75]
	s_mov_b32 m0, s96
	s_nop 0
	global_load_lds_dwordx4 v[234:235], off
	s_waitcnt vmcnt(8) lgkmcnt(0)
	s_barrier
	v_mfma_f32_16x16x32_bf16 v[126:129], v[134:137], v[190:193], v[126:129]
	v_mfma_f32_16x16x32_bf16 v[126:129], v[142:145], v[194:197], v[126:129]
	v_mfma_f32_16x16x32_bf16 v[122:125], v[146:149], v[190:193], v[122:125]
	v_mfma_f32_16x16x32_bf16 v[122:125], v[150:153], v[194:197], v[122:125]
	v_mfma_f32_16x16x32_bf16 v[110:113], v[134:137], v[198:201], v[110:113]
	v_mfma_f32_16x16x32_bf16 v[110:113], v[142:145], v[214:217], v[110:113]
	v_mfma_f32_16x16x32_bf16 v[106:109], v[146:149], v[198:201], v[106:109]
	v_mfma_f32_16x16x32_bf16 v[106:109], v[150:153], v[214:217], v[106:109]
	v_mfma_f32_16x16x32_bf16 v[94:97], v[134:137], v[218:221], v[94:97]
	v_mfma_f32_16x16x32_bf16 v[94:97], v[142:145], v[222:225], v[94:97]
	v_mfma_f32_16x16x32_bf16 v[90:93], v[146:149], v[218:221], v[90:93]
	v_mfma_f32_16x16x32_bf16 v[90:93], v[150:153], v[222:225], v[90:93]
	v_mfma_f32_16x16x32_bf16 v[78:81], v[134:137], v[226:229], v[78:81]
	v_mfma_f32_16x16x32_bf16 v[78:81], v[142:145], v[230:233], v[78:81]
	v_mfma_f32_16x16x32_bf16 v[74:77], v[146:149], v[226:229], v[74:77]
	v_mfma_f32_16x16x32_bf16 v[74:77], v[150:153], v[230:233], v[74:77]
	v_mfma_f32_16x16x32_bf16 v[118:121], v[154:157], v[190:193], v[118:121]
	v_mfma_f32_16x16x32_bf16 v[118:121], v[158:161], v[194:197], v[118:121]
	v_mfma_f32_16x16x32_bf16 v[114:117], v[182:185], v[190:193], v[114:117]
	v_mfma_f32_16x16x32_bf16 v[114:117], v[186:189], v[194:197], v[114:117]
	v_mfma_f32_16x16x32_bf16 v[102:105], v[154:157], v[198:201], v[102:105]
	v_mfma_f32_16x16x32_bf16 v[102:105], v[158:161], v[214:217], v[102:105]
	v_mfma_f32_16x16x32_bf16 v[98:101], v[182:185], v[198:201], v[98:101]
	v_mfma_f32_16x16x32_bf16 v[98:101], v[186:189], v[214:217], v[98:101]
	v_mfma_f32_16x16x32_bf16 v[86:89], v[154:157], v[218:221], v[86:89]
	v_mfma_f32_16x16x32_bf16 v[86:89], v[158:161], v[222:225], v[86:89]
	v_mfma_f32_16x16x32_bf16 v[82:85], v[182:185], v[218:221], v[82:85]
	v_mfma_f32_16x16x32_bf16 v[82:85], v[186:189], v[222:225], v[82:85]
	v_mfma_f32_16x16x32_bf16 v[70:73], v[154:157], v[226:229], v[70:73]
	v_mfma_f32_16x16x32_bf16 v[70:73], v[158:161], v[230:233], v[70:73]
	v_mfma_f32_16x16x32_bf16 v[66:69], v[182:185], v[226:229], v[66:69]
	v_mfma_f32_16x16x32_bf16 v[66:69], v[186:189], v[230:233], v[66:69]
	s_barrier
	ds_read_b128 v[190:193], v141 offset:49152
	ds_read_b128 v[194:197], v141 offset:50176
	ds_read_b128 v[198:201], v141 offset:51200
	ds_read_b128 v[214:217], v141 offset:52224
	ds_read_b128 v[218:221], v141 offset:53248
	ds_read_b128 v[222:225], v141 offset:54272
	ds_read_b128 v[226:229], v141 offset:55296
	ds_read_b128 v[230:233], v141 offset:56320
	s_add_i32 s20, s88, 0x18000
	s_mov_b32 m0, s20
	v_lshl_add_u64 v[234:235], v[162:163], 0, s[34:35]
	global_load_lds_dwordx4 v[234:235], off
	v_lshl_add_u64 v[234:235], v[162:163], 0, s[80:81]
	s_add_i32 m0, s20, 0x2000
	s_add_i32 s20, s88, 0x1c000
	global_load_lds_dwordx4 v[234:235], off
	v_lshl_add_u64 v[234:235], v[162:163], 0, s[38:39]
	s_mov_b32 m0, s20
	v_lshl_add_u64 v[162:163], v[162:163], 0, s[86:87]
	global_load_lds_dwordx4 v[234:235], off
	s_add_i32 m0, s20, 0x2000
	s_nop 0
	global_load_lds_dwordx4 v[162:163], off
	v_lshl_add_u64 v[162:163], v[202:203], 0, s[34:35]
	s_mov_b32 m0, s97
	s_nop 0
	global_load_lds_dwordx4 v[162:163], off
	v_lshl_add_u64 v[162:163], v[202:203], 0, s[80:81]
	s_mov_b32 m0, s58
	s_nop 0
	global_load_lds_dwordx4 v[162:163], off
	s_waitcnt vmcnt(8) lgkmcnt(0)
	s_barrier
	v_mfma_f32_16x16x32_bf16 v[62:65], v[134:137], v[190:193], v[62:65]
	v_mfma_f32_16x16x32_bf16 v[62:65], v[142:145], v[194:197], v[62:65]
	v_mfma_f32_16x16x32_bf16 v[58:61], v[146:149], v[190:193], v[58:61]
	v_mfma_f32_16x16x32_bf16 v[58:61], v[150:153], v[194:197], v[58:61]
	v_mfma_f32_16x16x32_bf16 v[46:49], v[134:137], v[198:201], v[46:49]
	v_mfma_f32_16x16x32_bf16 v[46:49], v[142:145], v[214:217], v[46:49]
	v_mfma_f32_16x16x32_bf16 v[42:45], v[146:149], v[198:201], v[42:45]
	v_mfma_f32_16x16x32_bf16 v[42:45], v[150:153], v[214:217], v[42:45]
	v_mfma_f32_16x16x32_bf16 v[30:33], v[134:137], v[218:221], v[30:33]
	v_mfma_f32_16x16x32_bf16 v[30:33], v[142:145], v[222:225], v[30:33]
	v_mfma_f32_16x16x32_bf16 v[26:29], v[146:149], v[218:221], v[26:29]
	v_mfma_f32_16x16x32_bf16 v[26:29], v[150:153], v[222:225], v[26:29]
	v_mfma_f32_16x16x32_bf16 v[14:17], v[134:137], v[226:229], v[14:17]
	v_mfma_f32_16x16x32_bf16 v[14:17], v[142:145], v[230:233], v[14:17]
	v_mfma_f32_16x16x32_bf16 v[10:13], v[146:149], v[226:229], v[10:13]
	v_mfma_f32_16x16x32_bf16 v[10:13], v[150:153], v[230:233], v[10:13]
	s_add_i32 s84, s84, 2
	s_add_u32 s6, s6, 0x100
	s_addc_u32 s7, s7, 0
	s_add_u32 s49, s49, 0x100
	s_addc_u32 s51, s51, 0
	v_mfma_f32_16x16x32_bf16 v[54:57], v[154:157], v[190:193], v[54:57]
	v_mfma_f32_16x16x32_bf16 v[54:57], v[158:161], v[194:197], v[54:57]
	v_mfma_f32_16x16x32_bf16 v[50:53], v[182:185], v[190:193], v[50:53]
	v_mfma_f32_16x16x32_bf16 v[50:53], v[186:189], v[194:197], v[50:53]
	v_mfma_f32_16x16x32_bf16 v[38:41], v[154:157], v[198:201], v[38:41]
	v_mfma_f32_16x16x32_bf16 v[38:41], v[158:161], v[214:217], v[38:41]
	v_mfma_f32_16x16x32_bf16 v[34:37], v[182:185], v[198:201], v[34:37]
	v_mfma_f32_16x16x32_bf16 v[34:37], v[186:189], v[214:217], v[34:37]
	v_mfma_f32_16x16x32_bf16 v[22:25], v[154:157], v[218:221], v[22:25]
	v_mfma_f32_16x16x32_bf16 v[22:25], v[158:161], v[222:225], v[22:25]
	v_mfma_f32_16x16x32_bf16 v[18:21], v[182:185], v[218:221], v[18:21]
	v_mfma_f32_16x16x32_bf16 v[18:21], v[186:189], v[222:225], v[18:21]
	v_mfma_f32_16x16x32_bf16 v[6:9], v[154:157], v[226:229], v[6:9]
	v_mfma_f32_16x16x32_bf16 v[6:9], v[158:161], v[230:233], v[6:9]
	v_mfma_f32_16x16x32_bf16 v[2:5], v[182:185], v[226:229], v[2:5]
	v_mfma_f32_16x16x32_bf16 v[2:5], v[186:189], v[230:233], v[2:5]
	s_barrier
	s_cmp_gt_u32 s84, 5
	s_cbranch_scc0 .LBB0_604
	s_setprio 0
	s_and_b64 vcc, exec, s[52:53]
	s_cbranch_vccz .LBB0_607
	s_barrier

.Lmid1_778:
	s_add_i32 m0, s43, 0xc000
	v_lshl_add_u64 v[202:203], s[76:77], 0, v[182:183]
	global_load_lds_dwordx4 v[202:203], off
	v_lshl_add_u64 v[202:203], v[202:203], 0, s[72:73]
	s_add_i32 m0, s43, 0xe000
	s_nop 0
	global_load_lds_dwordx4 v[202:203], off
	s_waitcnt vmcnt(8) lgkmcnt(0)
	s_barrier
	v_mfma_f32_16x16x32_bf16 v[126:129], v[130:133], v[184:187], 0
	v_mfma_f32_16x16x32_bf16 v[126:129], v[134:137], v[188:191], v[126:129]
	v_mfma_f32_16x16x32_bf16 v[122:125], v[138:141], v[184:187], 0
	v_mfma_f32_16x16x32_bf16 v[122:125], v[142:145], v[188:191], v[122:125]
	v_mfma_f32_16x16x32_bf16 v[110:113], v[130:133], v[198:201], 0
	v_mfma_f32_16x16x32_bf16 v[110:113], v[134:137], v[214:217], v[110:113]
	v_mfma_f32_16x16x32_bf16 v[106:109], v[138:141], v[198:201], 0
	v_mfma_f32_16x16x32_bf16 v[106:109], v[142:145], v[214:217], v[106:109]
	v_mfma_f32_16x16x32_bf16 v[94:97], v[130:133], v[218:221], 0
	v_mfma_f32_16x16x32_bf16 v[94:97], v[134:137], v[222:225], v[94:97]
	v_mfma_f32_16x16x32_bf16 v[90:93], v[138:141], v[218:221], 0
	v_mfma_f32_16x16x32_bf16 v[90:93], v[142:145], v[222:225], v[90:93]
	v_mfma_f32_16x16x32_bf16 v[78:81], v[130:133], v[226:229], 0
	v_mfma_f32_16x16x32_bf16 v[78:81], v[134:137], v[230:233], v[78:81]
	v_mfma_f32_16x16x32_bf16 v[74:77], v[138:141], v[226:229], 0
	v_mfma_f32_16x16x32_bf16 v[74:77], v[142:145], v[230:233], v[74:77]
	s_add_u32 s20, s76, 0xfffc0080
	s_addc_u32 s21, s77, -1
	s_cmp_eq_u32 vcc_hi, 12
	s_cselect_b32 s79, s61, s21
	s_cselect_b32 s78, s85, s20
	s_cselect_b32 s21, s59, vcc_lo
	s_cselect_b32 s20, s86, s87
	v_mfma_f32_16x16x32_bf16 v[118:121], v[146:149], v[184:187], 0
	v_mfma_f32_16x16x32_bf16 v[118:121], v[150:153], v[188:191], v[118:121]
	v_mfma_f32_16x16x32_bf16 v[114:117], v[154:157], v[184:187], 0
	v_mfma_f32_16x16x32_bf16 v[114:117], v[158:161], v[188:191], v[114:117]
	v_mfma_f32_16x16x32_bf16 v[102:105], v[146:149], v[198:201], 0
	v_mfma_f32_16x16x32_bf16 v[102:105], v[150:153], v[214:217], v[102:105]
	v_mfma_f32_16x16x32_bf16 v[98:101], v[154:157], v[198:201], 0
	v_mfma_f32_16x16x32_bf16 v[98:101], v[158:161], v[214:217], v[98:101]
	v_mfma_f32_16x16x32_bf16 v[86:89], v[146:149], v[218:221], 0
	v_mfma_f32_16x16x32_bf16 v[86:89], v[150:153], v[222:225], v[86:89]
	v_mfma_f32_16x16x32_bf16 v[82:85], v[154:157], v[218:221], 0
	v_mfma_f32_16x16x32_bf16 v[82:85], v[158:161], v[222:225], v[82:85]
	v_mfma_f32_16x16x32_bf16 v[70:73], v[146:149], v[226:229], 0
	v_mfma_f32_16x16x32_bf16 v[70:73], v[150:153], v[230:233], v[70:73]
	v_mfma_f32_16x16x32_bf16 v[66:69], v[154:157], v[226:229], 0
	v_mfma_f32_16x16x32_bf16 v[66:69], v[158:161], v[230:233], v[66:69]
	s_barrier
	ds_read_b128 v[184:187], v196 offset:16384
	ds_read_b128 v[188:191], v196 offset:17408
	ds_read_b128 v[198:201], v196 offset:18432
	ds_read_b128 v[214:217], v196 offset:19456
	ds_read_b128 v[218:221], v196 offset:20480
	ds_read_b128 v[222:225], v196 offset:21504
	ds_read_b128 v[226:229], v196 offset:22528
	ds_read_b128 v[230:233], v196 offset:23552
	v_lshl_add_u64 v[202:203], s[20:21], 0, v[0:1]
	s_add_i32 s20, s14, 0x10000
	s_mov_b32 m0, s20
	s_nop 0
	s_nop 0
	global_load_lds_dwordx4 v[202:203], off
	v_lshl_add_u64 v[234:235], v[202:203], 0, s[72:73]
	s_add_i32 m0, s20, 0x2000
	s_add_i32 s20, s14, 0x14000
	global_load_lds_dwordx4 v[234:235], off
	v_lshl_add_u64 v[234:235], v[202:203], 0, s[28:29]
	s_mov_b32 m0, s20
	s_nop 0
	global_load_lds_dwordx4 v[234:235], off
	v_lshl_add_u64 v[234:235], v[202:203], 0, s[82:83]
	s_add_i32 m0, s20, 0x2000
	s_nop 0
	global_load_lds_dwordx4 v[234:235], off
	v_lshl_add_u64 v[234:235], s[78:79], 0, v[162:163]
	s_mov_b32 m0, s43
	v_lshl_add_u64 v[236:237], v[234:235], 0, s[72:73]
	global_load_lds_dwordx4 v[234:235], off
	s_mov_b32 m0, s46
	s_nop 0
	global_load_lds_dwordx4 v[236:237], off
	s_waitcnt vmcnt(8) lgkmcnt(0)
	s_barrier
	v_mfma_f32_16x16x32_bf16 v[62:65], v[130:133], v[184:187], 0
	v_mfma_f32_16x16x32_bf16 v[62:65], v[134:137], v[188:191], v[62:65]
	v_mfma_f32_16x16x32_bf16 v[58:61], v[138:141], v[184:187], 0
	v_mfma_f32_16x16x32_bf16 v[58:61], v[142:145], v[188:191], v[58:61]
	v_mfma_f32_16x16x32_bf16 v[46:49], v[130:133], v[198:201], 0
	v_mfma_f32_16x16x32_bf16 v[46:49], v[134:137], v[214:217], v[46:49]
	v_mfma_f32_16x16x32_bf16 v[42:45], v[138:141], v[198:201], 0
	v_mfma_f32_16x16x32_bf16 v[42:45], v[142:145], v[214:217], v[42:45]
	v_mfma_f32_16x16x32_bf16 v[30:33], v[130:133], v[218:221], 0
	v_mfma_f32_16x16x32_bf16 v[30:33], v[134:137], v[222:225], v[30:33]
	v_mfma_f32_16x16x32_bf16 v[26:29], v[138:141], v[218:221], 0
	v_mfma_f32_16x16x32_bf16 v[26:29], v[142:145], v[222:225], v[26:29]
	v_mfma_f32_16x16x32_bf16 v[14:17], v[130:133], v[226:229], 0
	v_mfma_f32_16x16x32_bf16 v[14:17], v[134:137], v[230:233], v[14:17]
	v_mfma_f32_16x16x32_bf16 v[10:13], v[138:141], v[226:229], 0
	v_mfma_f32_16x16x32_bf16 v[10:13], v[142:145], v[230:233], v[10:13]
	v_mfma_f32_16x16x32_bf16 v[54:57], v[146:149], v[184:187], 0
	v_mfma_f32_16x16x32_bf16 v[54:57], v[150:153], v[188:191], v[54:57]
	v_mfma_f32_16x16x32_bf16 v[50:53], v[154:157], v[184:187], 0
	v_mfma_f32_16x16x32_bf16 v[50:53], v[158:161], v[188:191], v[50:53]
	v_mfma_f32_16x16x32_bf16 v[38:41], v[146:149], v[198:201], 0
	v_mfma_f32_16x16x32_bf16 v[38:41], v[150:153], v[214:217], v[38:41]
	v_mfma_f32_16x16x32_bf16 v[34:37], v[154:157], v[198:201], 0
	v_mfma_f32_16x16x32_bf16 v[34:37], v[158:161], v[214:217], v[34:37]
	v_mfma_f32_16x16x32_bf16 v[22:25], v[146:149], v[218:221], 0
	v_mfma_f32_16x16x32_bf16 v[22:25], v[150:153], v[222:225], v[22:25]
	v_mfma_f32_16x16x32_bf16 v[18:21], v[154:157], v[218:221], 0
	v_mfma_f32_16x16x32_bf16 v[18:21], v[158:161], v[222:225], v[18:21]
	v_mfma_f32_16x16x32_bf16 v[6:9], v[146:149], v[226:229], 0
	v_mfma_f32_16x16x32_bf16 v[6:9], v[150:153], v[230:233], v[6:9]
	v_mfma_f32_16x16x32_bf16 v[2:5], v[154:157], v[226:229], 0
	v_mfma_f32_16x16x32_bf16 v[2:5], v[158:161], v[230:233], v[2:5]
	s_barrier
	ds_read_b128 v[130:133], v243 offset:32768
	ds_read_b128 v[134:137], v243 offset:33792
	ds_read_b128 v[138:141], v243 offset:34816
	ds_read_b128 v[142:145], v243 offset:35840
	ds_read_b128 v[146:149], v243 offset:49152
	ds_read_b128 v[150:153], v243 offset:50176
	ds_read_b128 v[154:157], v243 offset:51200
	ds_read_b128 v[158:161], v243 offset:52224
	ds_read_b128 v[184:187], v196 offset:32768
	ds_read_b128 v[188:191], v196 offset:33792
	ds_read_b128 v[198:201], v196 offset:34816
	ds_read_b128 v[214:217], v196 offset:35840
	ds_read_b128 v[218:221], v196 offset:36864
	ds_read_b128 v[222:225], v196 offset:37888
	ds_read_b128 v[226:229], v196 offset:38912
	ds_read_b128 v[230:233], v196 offset:39936
	s_mov_b32 m0, s47
	v_lshl_add_u64 v[236:237], v[234:235], 0, s[28:29]
	global_load_lds_dwordx4 v[236:237], off
	v_lshl_add_u64 v[236:237], v[234:235], 0, s[82:83]
	s_mov_b32 m0, s88
	s_nop 0
	global_load_lds_dwordx4 v[236:237], off
	s_waitcnt vmcnt(8) lgkmcnt(0)
	s_barrier
	v_mfma_f32_16x16x32_bf16 v[126:129], v[130:133], v[184:187], v[126:129]
	v_mfma_f32_16x16x32_bf16 v[126:129], v[134:137], v[188:191], v[126:129]
	v_mfma_f32_16x16x32_bf16 v[122:125], v[138:141], v[184:187], v[122:125]
	v_mfma_f32_16x16x32_bf16 v[122:125], v[142:145], v[188:191], v[122:125]
	v_mfma_f32_16x16x32_bf16 v[110:113], v[130:133], v[198:201], v[110:113]
	v_mfma_f32_16x16x32_bf16 v[110:113], v[134:137], v[214:217], v[110:113]
	v_mfma_f32_16x16x32_bf16 v[106:109], v[138:141], v[198:201], v[106:109]
	v_mfma_f32_16x16x32_bf16 v[106:109], v[142:145], v[214:217], v[106:109]
	v_mfma_f32_16x16x32_bf16 v[94:97], v[130:133], v[218:221], v[94:97]
	v_mfma_f32_16x16x32_bf16 v[94:97], v[134:137], v[222:225], v[94:97]
	v_mfma_f32_16x16x32_bf16 v[90:93], v[138:141], v[218:221], v[90:93]
	v_mfma_f32_16x16x32_bf16 v[90:93], v[142:145], v[222:225], v[90:93]
	v_mfma_f32_16x16x32_bf16 v[78:81], v[130:133], v[226:229], v[78:81]
	v_mfma_f32_16x16x32_bf16 v[78:81], v[134:137], v[230:233], v[78:81]
	v_mfma_f32_16x16x32_bf16 v[74:77], v[138:141], v[226:229], v[74:77]
	v_mfma_f32_16x16x32_bf16 v[74:77], v[142:145], v[230:233], v[74:77]
	v_mfma_f32_16x16x32_bf16 v[118:121], v[146:149], v[184:187], v[118:121]
	v_mfma_f32_16x16x32_bf16 v[118:121], v[150:153], v[188:191], v[118:121]
	v_mfma_f32_16x16x32_bf16 v[114:117], v[154:157], v[184:187], v[114:117]
	v_mfma_f32_16x16x32_bf16 v[114:117], v[158:161], v[188:191], v[114:117]
	v_mfma_f32_16x16x32_bf16 v[102:105], v[146:149], v[198:201], v[102:105]
	v_mfma_f32_16x16x32_bf16 v[102:105], v[150:153], v[214:217], v[102:105]
	v_mfma_f32_16x16x32_bf16 v[98:101], v[154:157], v[198:201], v[98:101]
	v_mfma_f32_16x16x32_bf16 v[98:101], v[158:161], v[214:217], v[98:101]
	v_mfma_f32_16x16x32_bf16 v[86:89], v[146:149], v[218:221], v[86:89]
	v_mfma_f32_16x16x32_bf16 v[86:89], v[150:153], v[222:225], v[86:89]
	v_mfma_f32_16x16x32_bf16 v[82:85], v[154:157], v[218:221], v[82:85]
	v_mfma_f32_16x16x32_bf16 v[82:85], v[158:161], v[222:225], v[82:85]
	v_mfma_f32_16x16x32_bf16 v[70:73], v[146:149], v[226:229], v[70:73]
	v_mfma_f32_16x16x32_bf16 v[70:73], v[150:153], v[230:233], v[70:73]
	v_mfma_f32_16x16x32_bf16 v[66:69], v[154:157], v[226:229], v[66:69]
	v_mfma_f32_16x16x32_bf16 v[66:69], v[158:161], v[230:233], v[66:69]
	s_barrier
	ds_read_b128 v[184:187], v196 offset:49152
	ds_read_b128 v[188:191], v196 offset:50176
	ds_read_b128 v[198:201], v196 offset:51200
	ds_read_b128 v[214:217], v196 offset:52224
	ds_read_b128 v[218:221], v196 offset:53248
	ds_read_b128 v[222:225], v196 offset:54272
	ds_read_b128 v[226:229], v196 offset:55296
	ds_read_b128 v[230:233], v196 offset:56320
	s_add_i32 s20, s14, 0x18000
	s_mov_b32 m0, s20
	v_lshl_add_u64 v[236:237], v[202:203], 0, s[34:35]
	global_load_lds_dwordx4 v[236:237], off
	v_lshl_add_u64 v[236:237], v[202:203], 0, s[38:39]
	s_add_i32 m0, s20, 0x2000
	s_add_i32 s20, s14, 0x1c000
	global_load_lds_dwordx4 v[236:237], off
	v_lshl_add_u64 v[236:237], v[202:203], 0, s[44:45]
	s_mov_b32 m0, s20
	v_lshl_add_u64 v[202:203], v[202:203], 0, s[10:11]
	global_load_lds_dwordx4 v[236:237], off
	s_add_i32 m0, s20, 0x2000
	s_nop 0
	global_load_lds_dwordx4 v[202:203], off
	v_lshl_add_u64 v[202:203], v[234:235], 0, s[34:35]
	s_mov_b32 m0, s89
	s_nop 0
	global_load_lds_dwordx4 v[202:203], off
	v_lshl_add_u64 v[202:203], v[234:235], 0, s[38:39]
	s_mov_b32 m0, s90
	s_nop 0
	global_load_lds_dwordx4 v[202:203], off
	s_waitcnt vmcnt(8) lgkmcnt(0)
	s_barrier
	v_mfma_f32_16x16x32_bf16 v[62:65], v[130:133], v[184:187], v[62:65]
	v_mfma_f32_16x16x32_bf16 v[62:65], v[134:137], v[188:191], v[62:65]
	v_mfma_f32_16x16x32_bf16 v[58:61], v[138:141], v[184:187], v[58:61]
	v_mfma_f32_16x16x32_bf16 v[58:61], v[142:145], v[188:191], v[58:61]
	v_mfma_f32_16x16x32_bf16 v[46:49], v[130:133], v[198:201], v[46:49]
	v_mfma_f32_16x16x32_bf16 v[46:49], v[134:137], v[214:217], v[46:49]
	v_mfma_f32_16x16x32_bf16 v[42:45], v[138:141], v[198:201], v[42:45]
	v_mfma_f32_16x16x32_bf16 v[42:45], v[142:145], v[214:217], v[42:45]
	v_mfma_f32_16x16x32_bf16 v[30:33], v[130:133], v[218:221], v[30:33]
	v_mfma_f32_16x16x32_bf16 v[30:33], v[134:137], v[222:225], v[30:33]
	v_mfma_f32_16x16x32_bf16 v[26:29], v[138:141], v[218:221], v[26:29]
	v_mfma_f32_16x16x32_bf16 v[26:29], v[142:145], v[222:225], v[26:29]
	v_mfma_f32_16x16x32_bf16 v[14:17], v[130:133], v[226:229], v[14:17]
	v_mfma_f32_16x16x32_bf16 v[14:17], v[134:137], v[230:233], v[14:17]
	v_mfma_f32_16x16x32_bf16 v[10:13], v[138:141], v[226:229], v[10:13]
	v_mfma_f32_16x16x32_bf16 v[10:13], v[142:145], v[230:233], v[10:13]
	s_add_i32 vcc_hi, vcc_hi, 2
	s_add_u32 s76, s76, 0x100
	s_addc_u32 s77, s77, 0
	s_add_u32 s87, s87, 0x100
	s_addc_u32 vcc_lo, vcc_lo, 0
	v_mfma_f32_16x16x32_bf16 v[54:57], v[146:149], v[184:187], v[54:57]
	v_mfma_f32_16x16x32_bf16 v[54:57], v[150:153], v[188:191], v[54:57]
	v_mfma_f32_16x16x32_bf16 v[50:53], v[154:157], v[184:187], v[50:53]
	v_mfma_f32_16x16x32_bf16 v[50:53], v[158:161], v[188:191], v[50:53]
	v_mfma_f32_16x16x32_bf16 v[38:41], v[146:149], v[198:201], v[38:41]
	v_mfma_f32_16x16x32_bf16 v[38:41], v[150:153], v[214:217], v[38:41]
	v_mfma_f32_16x16x32_bf16 v[34:37], v[154:157], v[198:201], v[34:37]
	v_mfma_f32_16x16x32_bf16 v[34:37], v[158:161], v[214:217], v[34:37]
	v_mfma_f32_16x16x32_bf16 v[22:25], v[146:149], v[218:221], v[22:25]
	v_mfma_f32_16x16x32_bf16 v[22:25], v[150:153], v[222:225], v[22:25]
	v_mfma_f32_16x16x32_bf16 v[18:21], v[154:157], v[218:221], v[18:21]
	v_mfma_f32_16x16x32_bf16 v[18:21], v[158:161], v[222:225], v[18:21]
	v_mfma_f32_16x16x32_bf16 v[6:9], v[146:149], v[226:229], v[6:9]
	v_mfma_f32_16x16x32_bf16 v[6:9], v[150:153], v[230:233], v[6:9]
	v_mfma_f32_16x16x32_bf16 v[2:5], v[154:157], v[226:229], v[2:5]
	v_mfma_f32_16x16x32_bf16 v[2:5], v[158:161], v[230:233], v[2:5]
	s_barrier
	s_branch .LBB0_778
	.p2alignl 6, 3212836864
.LBB0_778:
	ds_read_b128 v[130:133], v243
	ds_read_b128 v[134:137], v243 offset:1024
	ds_read_b128 v[138:141], v243 offset:2048
	ds_read_b128 v[142:145], v243 offset:3072
	ds_read_b128 v[146:149], v243 offset:16384
	ds_read_b128 v[150:153], v243 offset:17408
	ds_read_b128 v[154:157], v243 offset:18432
	ds_read_b128 v[158:161], v243 offset:19456
	ds_read_b128 v[184:187], v196
	ds_read_b128 v[188:191], v196 offset:1024
	ds_read_b128 v[198:201], v196 offset:2048
	ds_read_b128 v[214:217], v196 offset:3072
	ds_read_b128 v[218:221], v196 offset:4096
	ds_read_b128 v[222:225], v196 offset:5120
	ds_read_b128 v[226:229], v196 offset:6144
	ds_read_b128 v[230:233], v196 offset:7168
	s_add_i32 m0, s43, 0xc000
	v_lshl_add_u64 v[202:203], s[76:77], 0, v[182:183]
	global_load_lds_dwordx4 v[202:203], off
	v_lshl_add_u64 v[202:203], v[202:203], 0, s[72:73]
	s_add_i32 m0, s43, 0xe000
	s_nop 0
	global_load_lds_dwordx4 v[202:203], off
	s_waitcnt vmcnt(8) lgkmcnt(0)
	s_barrier
	v_mfma_f32_16x16x32_bf16 v[126:129], v[130:133], v[184:187], v[126:129]
	v_mfma_f32_16x16x32_bf16 v[126:129], v[134:137], v[188:191], v[126:129]
	v_mfma_f32_16x16x32_bf16 v[122:125], v[138:141], v[184:187], v[122:125]
	v_mfma_f32_16x16x32_bf16 v[122:125], v[142:145], v[188:191], v[122:125]
	v_mfma_f32_16x16x32_bf16 v[110:113], v[130:133], v[198:201], v[110:113]
	v_mfma_f32_16x16x32_bf16 v[110:113], v[134:137], v[214:217], v[110:113]
	v_mfma_f32_16x16x32_bf16 v[106:109], v[138:141], v[198:201], v[106:109]
	v_mfma_f32_16x16x32_bf16 v[106:109], v[142:145], v[214:217], v[106:109]
	v_mfma_f32_16x16x32_bf16 v[94:97], v[130:133], v[218:221], v[94:97]
	v_mfma_f32_16x16x32_bf16 v[94:97], v[134:137], v[222:225], v[94:97]
	v_mfma_f32_16x16x32_bf16 v[90:93], v[138:141], v[218:221], v[90:93]
	v_mfma_f32_16x16x32_bf16 v[90:93], v[142:145], v[222:225], v[90:93]
	v_mfma_f32_16x16x32_bf16 v[78:81], v[130:133], v[226:229], v[78:81]
	v_mfma_f32_16x16x32_bf16 v[78:81], v[134:137], v[230:233], v[78:81]
	v_mfma_f32_16x16x32_bf16 v[74:77], v[138:141], v[226:229], v[74:77]
	v_mfma_f32_16x16x32_bf16 v[74:77], v[142:145], v[230:233], v[74:77]
	s_add_u32 s20, s76, 0xfffc0080
	s_addc_u32 s21, s77, -1
	s_cmp_eq_u32 vcc_hi, 12
	s_cselect_b32 s79, s61, s21
	s_cselect_b32 s78, s85, s20
	s_cselect_b32 s21, s59, vcc_lo
	s_cselect_b32 s20, s86, s87
	v_mfma_f32_16x16x32_bf16 v[118:121], v[146:149], v[184:187], v[118:121]
	v_mfma_f32_16x16x32_bf16 v[118:121], v[150:153], v[188:191], v[118:121]
	v_mfma_f32_16x16x32_bf16 v[114:117], v[154:157], v[184:187], v[114:117]
	v_mfma_f32_16x16x32_bf16 v[114:117], v[158:161], v[188:191], v[114:117]
	v_mfma_f32_16x16x32_bf16 v[102:105], v[146:149], v[198:201], v[102:105]
	v_mfma_f32_16x16x32_bf16 v[102:105], v[150:153], v[214:217], v[102:105]
	v_mfma_f32_16x16x32_bf16 v[98:101], v[154:157], v[198:201], v[98:101]
	v_mfma_f32_16x16x32_bf16 v[98:101], v[158:161], v[214:217], v[98:101]
	v_mfma_f32_16x16x32_bf16 v[86:89], v[146:149], v[218:221], v[86:89]
	v_mfma_f32_16x16x32_bf16 v[86:89], v[150:153], v[222:225], v[86:89]
	v_mfma_f32_16x16x32_bf16 v[82:85], v[154:157], v[218:221], v[82:85]
	v_mfma_f32_16x16x32_bf16 v[82:85], v[158:161], v[222:225], v[82:85]
	v_mfma_f32_16x16x32_bf16 v[70:73], v[146:149], v[226:229], v[70:73]
	v_mfma_f32_16x16x32_bf16 v[70:73], v[150:153], v[230:233], v[70:73]
	v_mfma_f32_16x16x32_bf16 v[66:69], v[154:157], v[226:229], v[66:69]
	v_mfma_f32_16x16x32_bf16 v[66:69], v[158:161], v[230:233], v[66:69]
	s_barrier
	ds_read_b128 v[184:187], v196 offset:16384
	ds_read_b128 v[188:191], v196 offset:17408
	ds_read_b128 v[198:201], v196 offset:18432
	ds_read_b128 v[214:217], v196 offset:19456
	ds_read_b128 v[218:221], v196 offset:20480
	ds_read_b128 v[222:225], v196 offset:21504
	ds_read_b128 v[226:229], v196 offset:22528
	ds_read_b128 v[230:233], v196 offset:23552
	v_lshl_add_u64 v[202:203], s[20:21], 0, v[0:1]
	s_add_i32 s20, s14, 0x10000
	s_mov_b32 m0, s20
	s_nop 0
	s_nop 0
	global_load_lds_dwordx4 v[202:203], off
	v_lshl_add_u64 v[234:235], v[202:203], 0, s[72:73]
	s_add_i32 m0, s20, 0x2000
	s_add_i32 s20, s14, 0x14000
	global_load_lds_dwordx4 v[234:235], off
	v_lshl_add_u64 v[234:235], v[202:203], 0, s[28:29]
	s_mov_b32 m0, s20
	s_nop 0
	global_load_lds_dwordx4 v[234:235], off
	v_lshl_add_u64 v[234:235], v[202:203], 0, s[82:83]
	s_add_i32 m0, s20, 0x2000
	s_nop 0
	global_load_lds_dwordx4 v[234:235], off
	v_lshl_add_u64 v[234:235], s[78:79], 0, v[162:163]
	s_mov_b32 m0, s43
	v_lshl_add_u64 v[236:237], v[234:235], 0, s[72:73]
	global_load_lds_dwordx4 v[234:235], off
	s_mov_b32 m0, s46
	s_nop 0
	global_load_lds_dwordx4 v[236:237], off
	s_waitcnt vmcnt(8) lgkmcnt(0)
	s_barrier
	v_mfma_f32_16x16x32_bf16 v[62:65], v[130:133], v[184:187], v[62:65]
	v_mfma_f32_16x16x32_bf16 v[62:65], v[134:137], v[188:191], v[62:65]
	v_mfma_f32_16x16x32_bf16 v[58:61], v[138:141], v[184:187], v[58:61]
	v_mfma_f32_16x16x32_bf16 v[58:61], v[142:145], v[188:191], v[58:61]
	v_mfma_f32_16x16x32_bf16 v[46:49], v[130:133], v[198:201], v[46:49]
	v_mfma_f32_16x16x32_bf16 v[46:49], v[134:137], v[214:217], v[46:49]
	v_mfma_f32_16x16x32_bf16 v[42:45], v[138:141], v[198:201], v[42:45]
	v_mfma_f32_16x16x32_bf16 v[42:45], v[142:145], v[214:217], v[42:45]
	v_mfma_f32_16x16x32_bf16 v[30:33], v[130:133], v[218:221], v[30:33]
	v_mfma_f32_16x16x32_bf16 v[30:33], v[134:137], v[222:225], v[30:33]
	v_mfma_f32_16x16x32_bf16 v[26:29], v[138:141], v[218:221], v[26:29]
	v_mfma_f32_16x16x32_bf16 v[26:29], v[142:145], v[222:225], v[26:29]
	v_mfma_f32_16x16x32_bf16 v[14:17], v[130:133], v[226:229], v[14:17]
	v_mfma_f32_16x16x32_bf16 v[14:17], v[134:137], v[230:233], v[14:17]
	v_mfma_f32_16x16x32_bf16 v[10:13], v[138:141], v[226:229], v[10:13]
	v_mfma_f32_16x16x32_bf16 v[10:13], v[142:145], v[230:233], v[10:13]
	v_mfma_f32_16x16x32_bf16 v[54:57], v[146:149], v[184:187], v[54:57]
	v_mfma_f32_16x16x32_bf16 v[54:57], v[150:153], v[188:191], v[54:57]
	v_mfma_f32_16x16x32_bf16 v[50:53], v[154:157], v[184:187], v[50:53]
	v_mfma_f32_16x16x32_bf16 v[50:53], v[158:161], v[188:191], v[50:53]
	v_mfma_f32_16x16x32_bf16 v[38:41], v[146:149], v[198:201], v[38:41]
	v_mfma_f32_16x16x32_bf16 v[38:41], v[150:153], v[214:217], v[38:41]
	v_mfma_f32_16x16x32_bf16 v[34:37], v[154:157], v[198:201], v[34:37]
	v_mfma_f32_16x16x32_bf16 v[34:37], v[158:161], v[214:217], v[34:37]
	v_mfma_f32_16x16x32_bf16 v[22:25], v[146:149], v[218:221], v[22:25]
	v_mfma_f32_16x16x32_bf16 v[22:25], v[150:153], v[222:225], v[22:25]
	v_mfma_f32_16x16x32_bf16 v[18:21], v[154:157], v[218:221], v[18:21]
	v_mfma_f32_16x16x32_bf16 v[18:21], v[158:161], v[222:225], v[18:21]
	v_mfma_f32_16x16x32_bf16 v[6:9], v[146:149], v[226:229], v[6:9]
	v_mfma_f32_16x16x32_bf16 v[6:9], v[150:153], v[230:233], v[6:9]
	v_mfma_f32_16x16x32_bf16 v[2:5], v[154:157], v[226:229], v[2:5]
	v_mfma_f32_16x16x32_bf16 v[2:5], v[158:161], v[230:233], v[2:5]
	s_barrier
	ds_read_b128 v[130:133], v243 offset:32768
	ds_read_b128 v[134:137], v243 offset:33792
	ds_read_b128 v[138:141], v243 offset:34816
	ds_read_b128 v[142:145], v243 offset:35840
	ds_read_b128 v[146:149], v243 offset:49152
	ds_read_b128 v[150:153], v243 offset:50176
	ds_read_b128 v[154:157], v243 offset:51200
	ds_read_b128 v[158:161], v243 offset:52224
	ds_read_b128 v[184:187], v196 offset:32768
	ds_read_b128 v[188:191], v196 offset:33792
	ds_read_b128 v[198:201], v196 offset:34816
	ds_read_b128 v[214:217], v196 offset:35840
	ds_read_b128 v[218:221], v196 offset:36864
	ds_read_b128 v[222:225], v196 offset:37888
	ds_read_b128 v[226:229], v196 offset:38912
	ds_read_b128 v[230:233], v196 offset:39936
	s_mov_b32 m0, s47
	v_lshl_add_u64 v[236:237], v[234:235], 0, s[28:29]
	global_load_lds_dwordx4 v[236:237], off
	v_lshl_add_u64 v[236:237], v[234:235], 0, s[82:83]
	s_mov_b32 m0, s88
	s_nop 0
	global_load_lds_dwordx4 v[236:237], off
	s_waitcnt vmcnt(8) lgkmcnt(0)
	s_barrier
	v_mfma_f32_16x16x32_bf16 v[126:129], v[130:133], v[184:187], v[126:129]
	v_mfma_f32_16x16x32_bf16 v[126:129], v[134:137], v[188:191], v[126:129]
	v_mfma_f32_16x16x32_bf16 v[122:125], v[138:141], v[184:187], v[122:125]
	v_mfma_f32_16x16x32_bf16 v[122:125], v[142:145], v[188:191], v[122:125]
	v_mfma_f32_16x16x32_bf16 v[110:113], v[130:133], v[198:201], v[110:113]
	v_mfma_f32_16x16x32_bf16 v[110:113], v[134:137], v[214:217], v[110:113]
	v_mfma_f32_16x16x32_bf16 v[106:109], v[138:141], v[198:201], v[106:109]
	v_mfma_f32_16x16x32_bf16 v[106:109], v[142:145], v[214:217], v[106:109]
	v_mfma_f32_16x16x32_bf16 v[94:97], v[130:133], v[218:221], v[94:97]
	v_mfma_f32_16x16x32_bf16 v[94:97], v[134:137], v[222:225], v[94:97]
	v_mfma_f32_16x16x32_bf16 v[90:93], v[138:141], v[218:221], v[90:93]
	v_mfma_f32_16x16x32_bf16 v[90:93], v[142:145], v[222:225], v[90:93]
	v_mfma_f32_16x16x32_bf16 v[78:81], v[130:133], v[226:229], v[78:81]
	v_mfma_f32_16x16x32_bf16 v[78:81], v[134:137], v[230:233], v[78:81]
	v_mfma_f32_16x16x32_bf16 v[74:77], v[138:141], v[226:229], v[74:77]
	v_mfma_f32_16x16x32_bf16 v[74:77], v[142:145], v[230:233], v[74:77]
	v_mfma_f32_16x16x32_bf16 v[118:121], v[146:149], v[184:187], v[118:121]
	v_mfma_f32_16x16x32_bf16 v[118:121], v[150:153], v[188:191], v[118:121]
	v_mfma_f32_16x16x32_bf16 v[114:117], v[154:157], v[184:187], v[114:117]
	v_mfma_f32_16x16x32_bf16 v[114:117], v[158:161], v[188:191], v[114:117]
	v_mfma_f32_16x16x32_bf16 v[102:105], v[146:149], v[198:201], v[102:105]
	v_mfma_f32_16x16x32_bf16 v[102:105], v[150:153], v[214:217], v[102:105]
	v_mfma_f32_16x16x32_bf16 v[98:101], v[154:157], v[198:201], v[98:101]
	v_mfma_f32_16x16x32_bf16 v[98:101], v[158:161], v[214:217], v[98:101]
	v_mfma_f32_16x16x32_bf16 v[86:89], v[146:149], v[218:221], v[86:89]
	v_mfma_f32_16x16x32_bf16 v[86:89], v[150:153], v[222:225], v[86:89]
	v_mfma_f32_16x16x32_bf16 v[82:85], v[154:157], v[218:221], v[82:85]
	v_mfma_f32_16x16x32_bf16 v[82:85], v[158:161], v[222:225], v[82:85]
	v_mfma_f32_16x16x32_bf16 v[70:73], v[146:149], v[226:229], v[70:73]
	v_mfma_f32_16x16x32_bf16 v[70:73], v[150:153], v[230:233], v[70:73]
	v_mfma_f32_16x16x32_bf16 v[66:69], v[154:157], v[226:229], v[66:69]
	v_mfma_f32_16x16x32_bf16 v[66:69], v[158:161], v[230:233], v[66:69]
	s_barrier
	ds_read_b128 v[184:187], v196 offset:49152
	ds_read_b128 v[188:191], v196 offset:50176
	ds_read_b128 v[198:201], v196 offset:51200
	ds_read_b128 v[214:217], v196 offset:52224
	ds_read_b128 v[218:221], v196 offset:53248
	ds_read_b128 v[222:225], v196 offset:54272
	ds_read_b128 v[226:229], v196 offset:55296
	ds_read_b128 v[230:233], v196 offset:56320
	s_add_i32 s20, s14, 0x18000
	s_mov_b32 m0, s20
	v_lshl_add_u64 v[236:237], v[202:203], 0, s[34:35]
	global_load_lds_dwordx4 v[236:237], off
	v_lshl_add_u64 v[236:237], v[202:203], 0, s[38:39]
	s_add_i32 m0, s20, 0x2000
	s_add_i32 s20, s14, 0x1c000
	global_load_lds_dwordx4 v[236:237], off
	v_lshl_add_u64 v[236:237], v[202:203], 0, s[44:45]
	s_mov_b32 m0, s20
	v_lshl_add_u64 v[202:203], v[202:203], 0, s[10:11]
	global_load_lds_dwordx4 v[236:237], off
	s_add_i32 m0, s20, 0x2000
	s_nop 0
	global_load_lds_dwordx4 v[202:203], off
	v_lshl_add_u64 v[202:203], v[234:235], 0, s[34:35]
	s_mov_b32 m0, s89
	s_nop 0
	global_load_lds_dwordx4 v[202:203], off
	v_lshl_add_u64 v[202:203], v[234:235], 0, s[38:39]
	s_mov_b32 m0, s90
	s_nop 0
	global_load_lds_dwordx4 v[202:203], off
	s_waitcnt vmcnt(8) lgkmcnt(0)
	s_barrier
	v_mfma_f32_16x16x32_bf16 v[62:65], v[130:133], v[184:187], v[62:65]
	v_mfma_f32_16x16x32_bf16 v[62:65], v[134:137], v[188:191], v[62:65]
	v_mfma_f32_16x16x32_bf16 v[58:61], v[138:141], v[184:187], v[58:61]
	v_mfma_f32_16x16x32_bf16 v[58:61], v[142:145], v[188:191], v[58:61]
	v_mfma_f32_16x16x32_bf16 v[46:49], v[130:133], v[198:201], v[46:49]
	v_mfma_f32_16x16x32_bf16 v[46:49], v[134:137], v[214:217], v[46:49]
	v_mfma_f32_16x16x32_bf16 v[42:45], v[138:141], v[198:201], v[42:45]
	v_mfma_f32_16x16x32_bf16 v[42:45], v[142:145], v[214:217], v[42:45]
	v_mfma_f32_16x16x32_bf16 v[30:33], v[130:133], v[218:221], v[30:33]
	v_mfma_f32_16x16x32_bf16 v[30:33], v[134:137], v[222:225], v[30:33]
	v_mfma_f32_16x16x32_bf16 v[26:29], v[138:141], v[218:221], v[26:29]
	v_mfma_f32_16x16x32_bf16 v[26:29], v[142:145], v[222:225], v[26:29]
	v_mfma_f32_16x16x32_bf16 v[14:17], v[130:133], v[226:229], v[14:17]
	v_mfma_f32_16x16x32_bf16 v[14:17], v[134:137], v[230:233], v[14:17]
	v_mfma_f32_16x16x32_bf16 v[10:13], v[138:141], v[226:229], v[10:13]
	v_mfma_f32_16x16x32_bf16 v[10:13], v[142:145], v[230:233], v[10:13]
	s_add_i32 vcc_hi, vcc_hi, 2
	s_add_u32 s76, s76, 0x100
	s_addc_u32 s77, s77, 0
	s_add_u32 s87, s87, 0x100
	s_addc_u32 vcc_lo, vcc_lo, 0
	v_mfma_f32_16x16x32_bf16 v[54:57], v[146:149], v[184:187], v[54:57]
	v_mfma_f32_16x16x32_bf16 v[54:57], v[150:153], v[188:191], v[54:57]
	v_mfma_f32_16x16x32_bf16 v[50:53], v[154:157], v[184:187], v[50:53]
	v_mfma_f32_16x16x32_bf16 v[50:53], v[158:161], v[188:191], v[50:53]
	v_mfma_f32_16x16x32_bf16 v[38:41], v[146:149], v[198:201], v[38:41]
	v_mfma_f32_16x16x32_bf16 v[38:41], v[150:153], v[214:217], v[38:41]
	v_mfma_f32_16x16x32_bf16 v[34:37], v[154:157], v[198:201], v[34:37]
	v_mfma_f32_16x16x32_bf16 v[34:37], v[158:161], v[214:217], v[34:37]
	v_mfma_f32_16x16x32_bf16 v[22:25], v[146:149], v[218:221], v[22:25]
	v_mfma_f32_16x16x32_bf16 v[22:25], v[150:153], v[222:225], v[22:25]
	v_mfma_f32_16x16x32_bf16 v[18:21], v[154:157], v[218:221], v[18:21]
	v_mfma_f32_16x16x32_bf16 v[18:21], v[158:161], v[222:225], v[18:21]
	v_mfma_f32_16x16x32_bf16 v[6:9], v[146:149], v[226:229], v[6:9]
	v_mfma_f32_16x16x32_bf16 v[6:9], v[150:153], v[230:233], v[6:9]
	v_mfma_f32_16x16x32_bf16 v[2:5], v[154:157], v[226:229], v[2:5]
	v_mfma_f32_16x16x32_bf16 v[2:5], v[158:161], v[230:233], v[2:5]
	s_barrier
	s_cmp_gt_u32 vcc_hi, 13
	s_cbranch_scc0 .LBB0_778
	s_setprio 0
	s_and_b64 vcc, exec, s[50:51]
	s_cbranch_vccz .LBB0_781
	s_barrier

.Lmid1_850:
	s_add_i32 m0, s15, 0xc000
	v_lshl_add_u64 v[142:143], s[56:57], 0, v[136:137]
	global_load_lds_dwordx4 v[142:143], off
	v_lshl_add_u64 v[142:143], v[142:143], 0, s[72:73]
	s_add_i32 m0, s15, 0xe000
	s_nop 0
	global_load_lds_dwordx4 v[142:143], off
	s_waitcnt vmcnt(8) lgkmcnt(0)
	s_barrier
	v_mfma_f32_16x16x32_bf16 v[126:129], v[138:141], v[198:201], 0
	v_mfma_f32_16x16x32_bf16 v[126:129], v[146:149], v[214:217], v[126:129]
	v_mfma_f32_16x16x32_bf16 v[122:125], v[150:153], v[198:201], 0
	v_mfma_f32_16x16x32_bf16 v[122:125], v[158:161], v[214:217], v[122:125]
	v_mfma_f32_16x16x32_bf16 v[110:113], v[138:141], v[218:221], 0
	v_mfma_f32_16x16x32_bf16 v[110:113], v[146:149], v[222:225], v[110:113]
	v_mfma_f32_16x16x32_bf16 v[106:109], v[150:153], v[218:221], 0
	v_mfma_f32_16x16x32_bf16 v[106:109], v[158:161], v[222:225], v[106:109]
	v_mfma_f32_16x16x32_bf16 v[94:97], v[138:141], v[226:229], 0
	v_mfma_f32_16x16x32_bf16 v[94:97], v[146:149], v[230:233], v[94:97]
	v_mfma_f32_16x16x32_bf16 v[90:93], v[150:153], v[226:229], 0
	v_mfma_f32_16x16x32_bf16 v[90:93], v[158:161], v[230:233], v[90:93]
	v_mfma_f32_16x16x32_bf16 v[78:81], v[138:141], v[234:237], 0
	v_mfma_f32_16x16x32_bf16 v[78:81], v[146:149], v[238:241], v[78:81]
	v_mfma_f32_16x16x32_bf16 v[74:77], v[150:153], v[234:237], 0
	v_mfma_f32_16x16x32_bf16 v[74:77], v[158:161], v[238:241], v[74:77]
	s_add_u32 s20, s56, 0xfffc0080
	s_addc_u32 s21, s57, -1
	s_cmp_eq_u32 s91, 12
	s_cselect_b32 s59, s76, s21
	s_cselect_b32 s58, s77, s20
	s_cselect_b32 s21, s69, s87
	s_cselect_b32 s20, s79, s86
	v_mfma_f32_16x16x32_bf16 v[118:121], v[182:185], v[198:201], 0
	v_mfma_f32_16x16x32_bf16 v[118:121], v[186:189], v[214:217], v[118:121]
	v_mfma_f32_16x16x32_bf16 v[114:117], v[190:193], v[198:201], 0
	v_mfma_f32_16x16x32_bf16 v[114:117], v[194:197], v[214:217], v[114:117]
	v_mfma_f32_16x16x32_bf16 v[102:105], v[182:185], v[218:221], 0
	v_mfma_f32_16x16x32_bf16 v[102:105], v[186:189], v[222:225], v[102:105]
	v_mfma_f32_16x16x32_bf16 v[98:101], v[190:193], v[218:221], 0
	v_mfma_f32_16x16x32_bf16 v[98:101], v[194:197], v[222:225], v[98:101]
	v_mfma_f32_16x16x32_bf16 v[86:89], v[182:185], v[226:229], 0
	v_mfma_f32_16x16x32_bf16 v[86:89], v[186:189], v[230:233], v[86:89]
	v_mfma_f32_16x16x32_bf16 v[82:85], v[190:193], v[226:229], 0
	v_mfma_f32_16x16x32_bf16 v[82:85], v[194:197], v[230:233], v[82:85]
	v_mfma_f32_16x16x32_bf16 v[70:73], v[182:185], v[234:237], 0
	v_mfma_f32_16x16x32_bf16 v[70:73], v[186:189], v[238:241], v[70:73]
	v_mfma_f32_16x16x32_bf16 v[66:69], v[190:193], v[234:237], 0
	v_mfma_f32_16x16x32_bf16 v[66:69], v[194:197], v[238:241], v[66:69]
	s_barrier
	ds_read_b128 v[198:201], v157 offset:16384
	ds_read_b128 v[214:217], v157 offset:17408
	ds_read_b128 v[218:221], v157 offset:18432
	ds_read_b128 v[222:225], v157 offset:19456
	ds_read_b128 v[226:229], v157 offset:20480
	ds_read_b128 v[230:233], v157 offset:21504
	ds_read_b128 v[234:237], v157 offset:22528
	ds_read_b128 v[238:241], v157 offset:23552
	v_lshl_add_u64 v[142:143], s[20:21], 0, v[130:131]
	s_add_i32 s20, s14, 0x10000
	s_mov_b32 m0, s20
	s_nop 0
	s_nop 0
	global_load_lds_dwordx4 v[142:143], off
	v_lshl_add_u64 v[162:163], v[142:143], 0, s[72:73]
	s_add_i32 m0, s20, 0x2000
	s_add_i32 s20, s14, 0x14000
	global_load_lds_dwordx4 v[162:163], off
	v_lshl_add_u64 v[162:163], v[142:143], 0, s[28:29]
	s_mov_b32 m0, s20
	s_nop 0
	global_load_lds_dwordx4 v[162:163], off
	v_lshl_add_u64 v[162:163], v[142:143], 0, s[82:83]
	s_add_i32 m0, s20, 0x2000
	s_nop 0
	global_load_lds_dwordx4 v[162:163], off
	v_lshl_add_u64 v[162:163], s[58:59], 0, v[132:133]
	s_mov_b32 m0, s15
	v_lshl_add_u64 v[202:203], v[162:163], 0, s[72:73]
	global_load_lds_dwordx4 v[162:163], off
	s_mov_b32 m0, s42
	s_nop 0
	global_load_lds_dwordx4 v[202:203], off
	s_waitcnt vmcnt(8) lgkmcnt(0)
	s_barrier
	v_mfma_f32_16x16x32_bf16 v[62:65], v[138:141], v[198:201], 0
	v_mfma_f32_16x16x32_bf16 v[62:65], v[146:149], v[214:217], v[62:65]
	v_mfma_f32_16x16x32_bf16 v[58:61], v[150:153], v[198:201], 0
	v_mfma_f32_16x16x32_bf16 v[58:61], v[158:161], v[214:217], v[58:61]
	v_mfma_f32_16x16x32_bf16 v[46:49], v[138:141], v[218:221], 0
	v_mfma_f32_16x16x32_bf16 v[46:49], v[146:149], v[222:225], v[46:49]
	v_mfma_f32_16x16x32_bf16 v[42:45], v[150:153], v[218:221], 0
	v_mfma_f32_16x16x32_bf16 v[42:45], v[158:161], v[222:225], v[42:45]
	v_mfma_f32_16x16x32_bf16 v[30:33], v[138:141], v[226:229], 0
	v_mfma_f32_16x16x32_bf16 v[30:33], v[146:149], v[230:233], v[30:33]
	v_mfma_f32_16x16x32_bf16 v[26:29], v[150:153], v[226:229], 0
	v_mfma_f32_16x16x32_bf16 v[26:29], v[158:161], v[230:233], v[26:29]
	v_mfma_f32_16x16x32_bf16 v[14:17], v[138:141], v[234:237], 0
	v_mfma_f32_16x16x32_bf16 v[14:17], v[146:149], v[238:241], v[14:17]
	v_mfma_f32_16x16x32_bf16 v[10:13], v[150:153], v[234:237], 0
	v_mfma_f32_16x16x32_bf16 v[10:13], v[158:161], v[238:241], v[10:13]
	v_mfma_f32_16x16x32_bf16 v[54:57], v[182:185], v[198:201], 0
	v_mfma_f32_16x16x32_bf16 v[54:57], v[186:189], v[214:217], v[54:57]
	v_mfma_f32_16x16x32_bf16 v[50:53], v[190:193], v[198:201], 0
	v_mfma_f32_16x16x32_bf16 v[50:53], v[194:197], v[214:217], v[50:53]
	v_mfma_f32_16x16x32_bf16 v[38:41], v[182:185], v[218:221], 0
	v_mfma_f32_16x16x32_bf16 v[38:41], v[186:189], v[222:225], v[38:41]
	v_mfma_f32_16x16x32_bf16 v[34:37], v[190:193], v[218:221], 0
	v_mfma_f32_16x16x32_bf16 v[34:37], v[194:197], v[222:225], v[34:37]
	v_mfma_f32_16x16x32_bf16 v[22:25], v[182:185], v[226:229], 0
	v_mfma_f32_16x16x32_bf16 v[22:25], v[186:189], v[230:233], v[22:25]
	v_mfma_f32_16x16x32_bf16 v[18:21], v[190:193], v[226:229], 0
	v_mfma_f32_16x16x32_bf16 v[18:21], v[194:197], v[230:233], v[18:21]
	v_mfma_f32_16x16x32_bf16 v[6:9], v[182:185], v[234:237], 0
	v_mfma_f32_16x16x32_bf16 v[6:9], v[186:189], v[238:241], v[6:9]
	v_mfma_f32_16x16x32_bf16 v[2:5], v[190:193], v[234:237], 0
	v_mfma_f32_16x16x32_bf16 v[2:5], v[194:197], v[238:241], v[2:5]
	s_barrier
	ds_read_b128 v[138:141], v243 offset:32768
	ds_read_b128 v[146:149], v243 offset:33792
	ds_read_b128 v[150:153], v243 offset:34816
	ds_read_b128 v[158:161], v243 offset:35840
	ds_read_b128 v[182:185], v243 offset:49152
	ds_read_b128 v[186:189], v243 offset:50176
	ds_read_b128 v[190:193], v243 offset:51200
	ds_read_b128 v[194:197], v243 offset:52224
	ds_read_b128 v[198:201], v157 offset:32768
	ds_read_b128 v[214:217], v157 offset:33792
	ds_read_b128 v[218:221], v157 offset:34816
	ds_read_b128 v[222:225], v157 offset:35840
	ds_read_b128 v[226:229], v157 offset:36864
	ds_read_b128 v[230:233], v157 offset:37888
	ds_read_b128 v[234:237], v157 offset:38912
	ds_read_b128 v[238:241], v157 offset:39936
	s_mov_b32 m0, s43
	v_lshl_add_u64 v[202:203], v[162:163], 0, s[28:29]
	global_load_lds_dwordx4 v[202:203], off
	v_lshl_add_u64 v[202:203], v[162:163], 0, s[82:83]
	s_mov_b32 m0, s46
	s_nop 0
	global_load_lds_dwordx4 v[202:203], off
	s_waitcnt vmcnt(8) lgkmcnt(0)
	s_barrier
	v_mfma_f32_16x16x32_bf16 v[126:129], v[138:141], v[198:201], v[126:129]
	v_mfma_f32_16x16x32_bf16 v[126:129], v[146:149], v[214:217], v[126:129]
	v_mfma_f32_16x16x32_bf16 v[122:125], v[150:153], v[198:201], v[122:125]
	v_mfma_f32_16x16x32_bf16 v[122:125], v[158:161], v[214:217], v[122:125]
	v_mfma_f32_16x16x32_bf16 v[110:113], v[138:141], v[218:221], v[110:113]
	v_mfma_f32_16x16x32_bf16 v[110:113], v[146:149], v[222:225], v[110:113]
	v_mfma_f32_16x16x32_bf16 v[106:109], v[150:153], v[218:221], v[106:109]
	v_mfma_f32_16x16x32_bf16 v[106:109], v[158:161], v[222:225], v[106:109]
	v_mfma_f32_16x16x32_bf16 v[94:97], v[138:141], v[226:229], v[94:97]
	v_mfma_f32_16x16x32_bf16 v[94:97], v[146:149], v[230:233], v[94:97]
	v_mfma_f32_16x16x32_bf16 v[90:93], v[150:153], v[226:229], v[90:93]
	v_mfma_f32_16x16x32_bf16 v[90:93], v[158:161], v[230:233], v[90:93]
	v_mfma_f32_16x16x32_bf16 v[78:81], v[138:141], v[234:237], v[78:81]
	v_mfma_f32_16x16x32_bf16 v[78:81], v[146:149], v[238:241], v[78:81]
	v_mfma_f32_16x16x32_bf16 v[74:77], v[150:153], v[234:237], v[74:77]
	v_mfma_f32_16x16x32_bf16 v[74:77], v[158:161], v[238:241], v[74:77]
	v_mfma_f32_16x16x32_bf16 v[118:121], v[182:185], v[198:201], v[118:121]
	v_mfma_f32_16x16x32_bf16 v[118:121], v[186:189], v[214:217], v[118:121]
	v_mfma_f32_16x16x32_bf16 v[114:117], v[190:193], v[198:201], v[114:117]
	v_mfma_f32_16x16x32_bf16 v[114:117], v[194:197], v[214:217], v[114:117]
	v_mfma_f32_16x16x32_bf16 v[102:105], v[182:185], v[218:221], v[102:105]
	v_mfma_f32_16x16x32_bf16 v[102:105], v[186:189], v[222:225], v[102:105]
	v_mfma_f32_16x16x32_bf16 v[98:101], v[190:193], v[218:221], v[98:101]
	v_mfma_f32_16x16x32_bf16 v[98:101], v[194:197], v[222:225], v[98:101]
	v_mfma_f32_16x16x32_bf16 v[86:89], v[182:185], v[226:229], v[86:89]
	v_mfma_f32_16x16x32_bf16 v[86:89], v[186:189], v[230:233], v[86:89]
	v_mfma_f32_16x16x32_bf16 v[82:85], v[190:193], v[226:229], v[82:85]
	v_mfma_f32_16x16x32_bf16 v[82:85], v[194:197], v[230:233], v[82:85]
	v_mfma_f32_16x16x32_bf16 v[70:73], v[182:185], v[234:237], v[70:73]
	v_mfma_f32_16x16x32_bf16 v[70:73], v[186:189], v[238:241], v[70:73]
	v_mfma_f32_16x16x32_bf16 v[66:69], v[190:193], v[234:237], v[66:69]
	v_mfma_f32_16x16x32_bf16 v[66:69], v[194:197], v[238:241], v[66:69]
	s_barrier
	ds_read_b128 v[198:201], v157 offset:49152
	ds_read_b128 v[214:217], v157 offset:50176
	ds_read_b128 v[218:221], v157 offset:51200
	ds_read_b128 v[222:225], v157 offset:52224
	ds_read_b128 v[226:229], v157 offset:53248
	ds_read_b128 v[230:233], v157 offset:54272
	ds_read_b128 v[234:237], v157 offset:55296
	ds_read_b128 v[238:241], v157 offset:56320
	s_add_i32 s20, s14, 0x18000
	s_mov_b32 m0, s20
	v_lshl_add_u64 v[202:203], v[142:143], 0, s[34:35]
	global_load_lds_dwordx4 v[202:203], off
	v_lshl_add_u64 v[202:203], v[142:143], 0, s[38:39]
	s_add_i32 m0, s20, 0x2000
	s_add_i32 s20, s14, 0x1c000
	global_load_lds_dwordx4 v[202:203], off
	v_lshl_add_u64 v[202:203], v[142:143], 0, s[44:45]
	s_mov_b32 m0, s20
	v_lshl_add_u64 v[142:143], v[142:143], 0, s[10:11]
	global_load_lds_dwordx4 v[202:203], off
	s_add_i32 m0, s20, 0x2000
	s_nop 0
	global_load_lds_dwordx4 v[142:143], off
	v_lshl_add_u64 v[142:143], v[162:163], 0, s[34:35]
	s_mov_b32 m0, s47
	s_nop 0
	global_load_lds_dwordx4 v[142:143], off
	v_lshl_add_u64 v[142:143], v[162:163], 0, s[38:39]
	s_mov_b32 m0, s96
	s_nop 0
	global_load_lds_dwordx4 v[142:143], off
	s_waitcnt vmcnt(8) lgkmcnt(0)
	s_barrier
	v_mfma_f32_16x16x32_bf16 v[62:65], v[138:141], v[198:201], v[62:65]
	v_mfma_f32_16x16x32_bf16 v[62:65], v[146:149], v[214:217], v[62:65]
	v_mfma_f32_16x16x32_bf16 v[58:61], v[150:153], v[198:201], v[58:61]
	v_mfma_f32_16x16x32_bf16 v[58:61], v[158:161], v[214:217], v[58:61]
	v_mfma_f32_16x16x32_bf16 v[46:49], v[138:141], v[218:221], v[46:49]
	v_mfma_f32_16x16x32_bf16 v[46:49], v[146:149], v[222:225], v[46:49]
	v_mfma_f32_16x16x32_bf16 v[42:45], v[150:153], v[218:221], v[42:45]
	v_mfma_f32_16x16x32_bf16 v[42:45], v[158:161], v[222:225], v[42:45]
	v_mfma_f32_16x16x32_bf16 v[30:33], v[138:141], v[226:229], v[30:33]
	v_mfma_f32_16x16x32_bf16 v[30:33], v[146:149], v[230:233], v[30:33]
	v_mfma_f32_16x16x32_bf16 v[26:29], v[150:153], v[226:229], v[26:29]
	v_mfma_f32_16x16x32_bf16 v[26:29], v[158:161], v[230:233], v[26:29]
	v_mfma_f32_16x16x32_bf16 v[14:17], v[138:141], v[234:237], v[14:17]
	v_mfma_f32_16x16x32_bf16 v[14:17], v[146:149], v[238:241], v[14:17]
	v_mfma_f32_16x16x32_bf16 v[10:13], v[150:153], v[234:237], v[10:13]
	v_mfma_f32_16x16x32_bf16 v[10:13], v[158:161], v[238:241], v[10:13]
	s_add_i32 s91, s91, 2
	s_add_u32 s56, s56, 0x100
	s_addc_u32 s57, s57, 0
	s_add_u32 s86, s86, 0x100
	s_addc_u32 s87, s87, 0
	v_mfma_f32_16x16x32_bf16 v[54:57], v[182:185], v[198:201], v[54:57]
	v_mfma_f32_16x16x32_bf16 v[54:57], v[186:189], v[214:217], v[54:57]
	v_mfma_f32_16x16x32_bf16 v[50:53], v[190:193], v[198:201], v[50:53]
	v_mfma_f32_16x16x32_bf16 v[50:53], v[194:197], v[214:217], v[50:53]
	v_mfma_f32_16x16x32_bf16 v[38:41], v[182:185], v[218:221], v[38:41]
	v_mfma_f32_16x16x32_bf16 v[38:41], v[186:189], v[222:225], v[38:41]
	v_mfma_f32_16x16x32_bf16 v[34:37], v[190:193], v[218:221], v[34:37]
	v_mfma_f32_16x16x32_bf16 v[34:37], v[194:197], v[222:225], v[34:37]
	v_mfma_f32_16x16x32_bf16 v[22:25], v[182:185], v[226:229], v[22:25]
	v_mfma_f32_16x16x32_bf16 v[22:25], v[186:189], v[230:233], v[22:25]
	v_mfma_f32_16x16x32_bf16 v[18:21], v[190:193], v[226:229], v[18:21]
	v_mfma_f32_16x16x32_bf16 v[18:21], v[194:197], v[230:233], v[18:21]
	v_mfma_f32_16x16x32_bf16 v[6:9], v[182:185], v[234:237], v[6:9]
	v_mfma_f32_16x16x32_bf16 v[6:9], v[186:189], v[238:241], v[6:9]
	v_mfma_f32_16x16x32_bf16 v[2:5], v[190:193], v[234:237], v[2:5]
	v_mfma_f32_16x16x32_bf16 v[2:5], v[194:197], v[238:241], v[2:5]
	s_barrier
	s_branch .LBB0_850
	.p2alignl 6, 3212836864
.LBB0_850:
	ds_read_b128 v[138:141], v243
	ds_read_b128 v[146:149], v243 offset:1024
	ds_read_b128 v[150:153], v243 offset:2048
	ds_read_b128 v[158:161], v243 offset:3072
	ds_read_b128 v[182:185], v243 offset:16384
	ds_read_b128 v[186:189], v243 offset:17408
	ds_read_b128 v[190:193], v243 offset:18432
	ds_read_b128 v[194:197], v243 offset:19456
	ds_read_b128 v[198:201], v157
	ds_read_b128 v[214:217], v157 offset:1024
	ds_read_b128 v[218:221], v157 offset:2048
	ds_read_b128 v[222:225], v157 offset:3072
	ds_read_b128 v[226:229], v157 offset:4096
	ds_read_b128 v[230:233], v157 offset:5120
	ds_read_b128 v[234:237], v157 offset:6144
	ds_read_b128 v[238:241], v157 offset:7168
	s_add_i32 m0, s15, 0xc000
	v_lshl_add_u64 v[142:143], s[56:57], 0, v[136:137]
	global_load_lds_dwordx4 v[142:143], off
	v_lshl_add_u64 v[142:143], v[142:143], 0, s[72:73]
	s_add_i32 m0, s15, 0xe000
	s_nop 0
	global_load_lds_dwordx4 v[142:143], off
	s_waitcnt vmcnt(8) lgkmcnt(0)
	s_barrier
	v_mfma_f32_16x16x32_bf16 v[126:129], v[138:141], v[198:201], v[126:129]
	v_mfma_f32_16x16x32_bf16 v[126:129], v[146:149], v[214:217], v[126:129]
	v_mfma_f32_16x16x32_bf16 v[122:125], v[150:153], v[198:201], v[122:125]
	v_mfma_f32_16x16x32_bf16 v[122:125], v[158:161], v[214:217], v[122:125]
	v_mfma_f32_16x16x32_bf16 v[110:113], v[138:141], v[218:221], v[110:113]
	v_mfma_f32_16x16x32_bf16 v[110:113], v[146:149], v[222:225], v[110:113]
	v_mfma_f32_16x16x32_bf16 v[106:109], v[150:153], v[218:221], v[106:109]
	v_mfma_f32_16x16x32_bf16 v[106:109], v[158:161], v[222:225], v[106:109]
	v_mfma_f32_16x16x32_bf16 v[94:97], v[138:141], v[226:229], v[94:97]
	v_mfma_f32_16x16x32_bf16 v[94:97], v[146:149], v[230:233], v[94:97]
	v_mfma_f32_16x16x32_bf16 v[90:93], v[150:153], v[226:229], v[90:93]
	v_mfma_f32_16x16x32_bf16 v[90:93], v[158:161], v[230:233], v[90:93]
	v_mfma_f32_16x16x32_bf16 v[78:81], v[138:141], v[234:237], v[78:81]
	v_mfma_f32_16x16x32_bf16 v[78:81], v[146:149], v[238:241], v[78:81]
	v_mfma_f32_16x16x32_bf16 v[74:77], v[150:153], v[234:237], v[74:77]
	v_mfma_f32_16x16x32_bf16 v[74:77], v[158:161], v[238:241], v[74:77]
	s_add_u32 s20, s56, 0xfffc0080
	s_addc_u32 s21, s57, -1
	s_cmp_eq_u32 s91, 12
	s_cselect_b32 s59, s76, s21
	s_cselect_b32 s58, s77, s20
	s_cselect_b32 s21, s69, s87
	s_cselect_b32 s20, s79, s86
	v_mfma_f32_16x16x32_bf16 v[118:121], v[182:185], v[198:201], v[118:121]
	v_mfma_f32_16x16x32_bf16 v[118:121], v[186:189], v[214:217], v[118:121]
	v_mfma_f32_16x16x32_bf16 v[114:117], v[190:193], v[198:201], v[114:117]
	v_mfma_f32_16x16x32_bf16 v[114:117], v[194:197], v[214:217], v[114:117]
	v_mfma_f32_16x16x32_bf16 v[102:105], v[182:185], v[218:221], v[102:105]
	v_mfma_f32_16x16x32_bf16 v[102:105], v[186:189], v[222:225], v[102:105]
	v_mfma_f32_16x16x32_bf16 v[98:101], v[190:193], v[218:221], v[98:101]
	v_mfma_f32_16x16x32_bf16 v[98:101], v[194:197], v[222:225], v[98:101]
	v_mfma_f32_16x16x32_bf16 v[86:89], v[182:185], v[226:229], v[86:89]
	v_mfma_f32_16x16x32_bf16 v[86:89], v[186:189], v[230:233], v[86:89]
	v_mfma_f32_16x16x32_bf16 v[82:85], v[190:193], v[226:229], v[82:85]
	v_mfma_f32_16x16x32_bf16 v[82:85], v[194:197], v[230:233], v[82:85]
	v_mfma_f32_16x16x32_bf16 v[70:73], v[182:185], v[234:237], v[70:73]
	v_mfma_f32_16x16x32_bf16 v[70:73], v[186:189], v[238:241], v[70:73]
	v_mfma_f32_16x16x32_bf16 v[66:69], v[190:193], v[234:237], v[66:69]
	v_mfma_f32_16x16x32_bf16 v[66:69], v[194:197], v[238:241], v[66:69]
	s_barrier
	ds_read_b128 v[198:201], v157 offset:16384
	ds_read_b128 v[214:217], v157 offset:17408
	ds_read_b128 v[218:221], v157 offset:18432
	ds_read_b128 v[222:225], v157 offset:19456
	ds_read_b128 v[226:229], v157 offset:20480
	ds_read_b128 v[230:233], v157 offset:21504
	ds_read_b128 v[234:237], v157 offset:22528
	ds_read_b128 v[238:241], v157 offset:23552
	v_lshl_add_u64 v[142:143], s[20:21], 0, v[130:131]
	s_add_i32 s20, s14, 0x10000
	s_mov_b32 m0, s20
	s_nop 0
	s_nop 0
	global_load_lds_dwordx4 v[142:143], off
	v_lshl_add_u64 v[162:163], v[142:143], 0, s[72:73]
	s_add_i32 m0, s20, 0x2000
	s_add_i32 s20, s14, 0x14000
	global_load_lds_dwordx4 v[162:163], off
	v_lshl_add_u64 v[162:163], v[142:143], 0, s[28:29]
	s_mov_b32 m0, s20
	s_nop 0
	global_load_lds_dwordx4 v[162:163], off
	v_lshl_add_u64 v[162:163], v[142:143], 0, s[82:83]
	s_add_i32 m0, s20, 0x2000
	s_nop 0
	global_load_lds_dwordx4 v[162:163], off
	v_lshl_add_u64 v[162:163], s[58:59], 0, v[132:133]
	s_mov_b32 m0, s15
	v_lshl_add_u64 v[202:203], v[162:163], 0, s[72:73]
	global_load_lds_dwordx4 v[162:163], off
	s_mov_b32 m0, s42
	s_nop 0
	global_load_lds_dwordx4 v[202:203], off
	s_waitcnt vmcnt(8) lgkmcnt(0)
	s_barrier
	v_mfma_f32_16x16x32_bf16 v[62:65], v[138:141], v[198:201], v[62:65]
	v_mfma_f32_16x16x32_bf16 v[62:65], v[146:149], v[214:217], v[62:65]
	v_mfma_f32_16x16x32_bf16 v[58:61], v[150:153], v[198:201], v[58:61]
	v_mfma_f32_16x16x32_bf16 v[58:61], v[158:161], v[214:217], v[58:61]
	v_mfma_f32_16x16x32_bf16 v[46:49], v[138:141], v[218:221], v[46:49]
	v_mfma_f32_16x16x32_bf16 v[46:49], v[146:149], v[222:225], v[46:49]
	v_mfma_f32_16x16x32_bf16 v[42:45], v[150:153], v[218:221], v[42:45]
	v_mfma_f32_16x16x32_bf16 v[42:45], v[158:161], v[222:225], v[42:45]
	v_mfma_f32_16x16x32_bf16 v[30:33], v[138:141], v[226:229], v[30:33]
	v_mfma_f32_16x16x32_bf16 v[30:33], v[146:149], v[230:233], v[30:33]
	v_mfma_f32_16x16x32_bf16 v[26:29], v[150:153], v[226:229], v[26:29]
	v_mfma_f32_16x16x32_bf16 v[26:29], v[158:161], v[230:233], v[26:29]
	v_mfma_f32_16x16x32_bf16 v[14:17], v[138:141], v[234:237], v[14:17]
	v_mfma_f32_16x16x32_bf16 v[14:17], v[146:149], v[238:241], v[14:17]
	v_mfma_f32_16x16x32_bf16 v[10:13], v[150:153], v[234:237], v[10:13]
	v_mfma_f32_16x16x32_bf16 v[10:13], v[158:161], v[238:241], v[10:13]
	v_mfma_f32_16x16x32_bf16 v[54:57], v[182:185], v[198:201], v[54:57]
	v_mfma_f32_16x16x32_bf16 v[54:57], v[186:189], v[214:217], v[54:57]
	v_mfma_f32_16x16x32_bf16 v[50:53], v[190:193], v[198:201], v[50:53]
	v_mfma_f32_16x16x32_bf16 v[50:53], v[194:197], v[214:217], v[50:53]
	v_mfma_f32_16x16x32_bf16 v[38:41], v[182:185], v[218:221], v[38:41]
	v_mfma_f32_16x16x32_bf16 v[38:41], v[186:189], v[222:225], v[38:41]
	v_mfma_f32_16x16x32_bf16 v[34:37], v[190:193], v[218:221], v[34:37]
	v_mfma_f32_16x16x32_bf16 v[34:37], v[194:197], v[222:225], v[34:37]
	v_mfma_f32_16x16x32_bf16 v[22:25], v[182:185], v[226:229], v[22:25]
	v_mfma_f32_16x16x32_bf16 v[22:25], v[186:189], v[230:233], v[22:25]
	v_mfma_f32_16x16x32_bf16 v[18:21], v[190:193], v[226:229], v[18:21]
	v_mfma_f32_16x16x32_bf16 v[18:21], v[194:197], v[230:233], v[18:21]
	v_mfma_f32_16x16x32_bf16 v[6:9], v[182:185], v[234:237], v[6:9]
	v_mfma_f32_16x16x32_bf16 v[6:9], v[186:189], v[238:241], v[6:9]
	v_mfma_f32_16x16x32_bf16 v[2:5], v[190:193], v[234:237], v[2:5]
	v_mfma_f32_16x16x32_bf16 v[2:5], v[194:197], v[238:241], v[2:5]
	s_barrier
	ds_read_b128 v[138:141], v243 offset:32768
	ds_read_b128 v[146:149], v243 offset:33792
	ds_read_b128 v[150:153], v243 offset:34816
	ds_read_b128 v[158:161], v243 offset:35840
	ds_read_b128 v[182:185], v243 offset:49152
	ds_read_b128 v[186:189], v243 offset:50176
	ds_read_b128 v[190:193], v243 offset:51200
	ds_read_b128 v[194:197], v243 offset:52224
	ds_read_b128 v[198:201], v157 offset:32768
	ds_read_b128 v[214:217], v157 offset:33792
	ds_read_b128 v[218:221], v157 offset:34816
	ds_read_b128 v[222:225], v157 offset:35840
	ds_read_b128 v[226:229], v157 offset:36864
	ds_read_b128 v[230:233], v157 offset:37888
	ds_read_b128 v[234:237], v157 offset:38912
	ds_read_b128 v[238:241], v157 offset:39936
	s_mov_b32 m0, s43
	v_lshl_add_u64 v[202:203], v[162:163], 0, s[28:29]
	global_load_lds_dwordx4 v[202:203], off
	v_lshl_add_u64 v[202:203], v[162:163], 0, s[82:83]
	s_mov_b32 m0, s46
	s_nop 0
	global_load_lds_dwordx4 v[202:203], off
	s_waitcnt vmcnt(8) lgkmcnt(0)
	s_barrier
	v_mfma_f32_16x16x32_bf16 v[126:129], v[138:141], v[198:201], v[126:129]
	v_mfma_f32_16x16x32_bf16 v[126:129], v[146:149], v[214:217], v[126:129]
	v_mfma_f32_16x16x32_bf16 v[122:125], v[150:153], v[198:201], v[122:125]
	v_mfma_f32_16x16x32_bf16 v[122:125], v[158:161], v[214:217], v[122:125]
	v_mfma_f32_16x16x32_bf16 v[110:113], v[138:141], v[218:221], v[110:113]
	v_mfma_f32_16x16x32_bf16 v[110:113], v[146:149], v[222:225], v[110:113]
	v_mfma_f32_16x16x32_bf16 v[106:109], v[150:153], v[218:221], v[106:109]
	v_mfma_f32_16x16x32_bf16 v[106:109], v[158:161], v[222:225], v[106:109]
	v_mfma_f32_16x16x32_bf16 v[94:97], v[138:141], v[226:229], v[94:97]
	v_mfma_f32_16x16x32_bf16 v[94:97], v[146:149], v[230:233], v[94:97]
	v_mfma_f32_16x16x32_bf16 v[90:93], v[150:153], v[226:229], v[90:93]
	v_mfma_f32_16x16x32_bf16 v[90:93], v[158:161], v[230:233], v[90:93]
	v_mfma_f32_16x16x32_bf16 v[78:81], v[138:141], v[234:237], v[78:81]
	v_mfma_f32_16x16x32_bf16 v[78:81], v[146:149], v[238:241], v[78:81]
	v_mfma_f32_16x16x32_bf16 v[74:77], v[150:153], v[234:237], v[74:77]
	v_mfma_f32_16x16x32_bf16 v[74:77], v[158:161], v[238:241], v[74:77]
	v_mfma_f32_16x16x32_bf16 v[118:121], v[182:185], v[198:201], v[118:121]
	v_mfma_f32_16x16x32_bf16 v[118:121], v[186:189], v[214:217], v[118:121]
	v_mfma_f32_16x16x32_bf16 v[114:117], v[190:193], v[198:201], v[114:117]
	v_mfma_f32_16x16x32_bf16 v[114:117], v[194:197], v[214:217], v[114:117]
	v_mfma_f32_16x16x32_bf16 v[102:105], v[182:185], v[218:221], v[102:105]
	v_mfma_f32_16x16x32_bf16 v[102:105], v[186:189], v[222:225], v[102:105]
	v_mfma_f32_16x16x32_bf16 v[98:101], v[190:193], v[218:221], v[98:101]
	v_mfma_f32_16x16x32_bf16 v[98:101], v[194:197], v[222:225], v[98:101]
	v_mfma_f32_16x16x32_bf16 v[86:89], v[182:185], v[226:229], v[86:89]
	v_mfma_f32_16x16x32_bf16 v[86:89], v[186:189], v[230:233], v[86:89]
	v_mfma_f32_16x16x32_bf16 v[82:85], v[190:193], v[226:229], v[82:85]
	v_mfma_f32_16x16x32_bf16 v[82:85], v[194:197], v[230:233], v[82:85]
	v_mfma_f32_16x16x32_bf16 v[70:73], v[182:185], v[234:237], v[70:73]
	v_mfma_f32_16x16x32_bf16 v[70:73], v[186:189], v[238:241], v[70:73]
	v_mfma_f32_16x16x32_bf16 v[66:69], v[190:193], v[234:237], v[66:69]
	v_mfma_f32_16x16x32_bf16 v[66:69], v[194:197], v[238:241], v[66:69]
	s_barrier
	ds_read_b128 v[198:201], v157 offset:49152
	ds_read_b128 v[214:217], v157 offset:50176
	ds_read_b128 v[218:221], v157 offset:51200
	ds_read_b128 v[222:225], v157 offset:52224
	ds_read_b128 v[226:229], v157 offset:53248
	ds_read_b128 v[230:233], v157 offset:54272
	ds_read_b128 v[234:237], v157 offset:55296
	ds_read_b128 v[238:241], v157 offset:56320
	s_add_i32 s20, s14, 0x18000
	s_mov_b32 m0, s20
	v_lshl_add_u64 v[202:203], v[142:143], 0, s[34:35]
	global_load_lds_dwordx4 v[202:203], off
	v_lshl_add_u64 v[202:203], v[142:143], 0, s[38:39]
	s_add_i32 m0, s20, 0x2000
	s_add_i32 s20, s14, 0x1c000
	global_load_lds_dwordx4 v[202:203], off
	v_lshl_add_u64 v[202:203], v[142:143], 0, s[44:45]
	s_mov_b32 m0, s20
	v_lshl_add_u64 v[142:143], v[142:143], 0, s[10:11]
	global_load_lds_dwordx4 v[202:203], off
	s_add_i32 m0, s20, 0x2000
	s_nop 0
	global_load_lds_dwordx4 v[142:143], off
	v_lshl_add_u64 v[142:143], v[162:163], 0, s[34:35]
	s_mov_b32 m0, s47
	s_nop 0
	global_load_lds_dwordx4 v[142:143], off
	v_lshl_add_u64 v[142:143], v[162:163], 0, s[38:39]
	s_mov_b32 m0, s96
	s_nop 0
	global_load_lds_dwordx4 v[142:143], off
	s_waitcnt vmcnt(8) lgkmcnt(0)
	s_barrier
	v_mfma_f32_16x16x32_bf16 v[62:65], v[138:141], v[198:201], v[62:65]
	v_mfma_f32_16x16x32_bf16 v[62:65], v[146:149], v[214:217], v[62:65]
	v_mfma_f32_16x16x32_bf16 v[58:61], v[150:153], v[198:201], v[58:61]
	v_mfma_f32_16x16x32_bf16 v[58:61], v[158:161], v[214:217], v[58:61]
	v_mfma_f32_16x16x32_bf16 v[46:49], v[138:141], v[218:221], v[46:49]
	v_mfma_f32_16x16x32_bf16 v[46:49], v[146:149], v[222:225], v[46:49]
	v_mfma_f32_16x16x32_bf16 v[42:45], v[150:153], v[218:221], v[42:45]
	v_mfma_f32_16x16x32_bf16 v[42:45], v[158:161], v[222:225], v[42:45]
	v_mfma_f32_16x16x32_bf16 v[30:33], v[138:141], v[226:229], v[30:33]
	v_mfma_f32_16x16x32_bf16 v[30:33], v[146:149], v[230:233], v[30:33]
	v_mfma_f32_16x16x32_bf16 v[26:29], v[150:153], v[226:229], v[26:29]
	v_mfma_f32_16x16x32_bf16 v[26:29], v[158:161], v[230:233], v[26:29]
	v_mfma_f32_16x16x32_bf16 v[14:17], v[138:141], v[234:237], v[14:17]
	v_mfma_f32_16x16x32_bf16 v[14:17], v[146:149], v[238:241], v[14:17]
	v_mfma_f32_16x16x32_bf16 v[10:13], v[150:153], v[234:237], v[10:13]
	v_mfma_f32_16x16x32_bf16 v[10:13], v[158:161], v[238:241], v[10:13]
	s_add_i32 s91, s91, 2
	s_add_u32 s56, s56, 0x100
	s_addc_u32 s57, s57, 0
	s_add_u32 s86, s86, 0x100
	s_addc_u32 s87, s87, 0
	v_mfma_f32_16x16x32_bf16 v[54:57], v[182:185], v[198:201], v[54:57]
	v_mfma_f32_16x16x32_bf16 v[54:57], v[186:189], v[214:217], v[54:57]
	v_mfma_f32_16x16x32_bf16 v[50:53], v[190:193], v[198:201], v[50:53]
	v_mfma_f32_16x16x32_bf16 v[50:53], v[194:197], v[214:217], v[50:53]
	v_mfma_f32_16x16x32_bf16 v[38:41], v[182:185], v[218:221], v[38:41]
	v_mfma_f32_16x16x32_bf16 v[38:41], v[186:189], v[222:225], v[38:41]
	v_mfma_f32_16x16x32_bf16 v[34:37], v[190:193], v[218:221], v[34:37]
	v_mfma_f32_16x16x32_bf16 v[34:37], v[194:197], v[222:225], v[34:37]
	v_mfma_f32_16x16x32_bf16 v[22:25], v[182:185], v[226:229], v[22:25]
	v_mfma_f32_16x16x32_bf16 v[22:25], v[186:189], v[230:233], v[22:25]
	v_mfma_f32_16x16x32_bf16 v[18:21], v[190:193], v[226:229], v[18:21]
	v_mfma_f32_16x16x32_bf16 v[18:21], v[194:197], v[230:233], v[18:21]
	v_mfma_f32_16x16x32_bf16 v[6:9], v[182:185], v[234:237], v[6:9]
	v_mfma_f32_16x16x32_bf16 v[6:9], v[186:189], v[238:241], v[6:9]
	v_mfma_f32_16x16x32_bf16 v[2:5], v[190:193], v[234:237], v[2:5]
	v_mfma_f32_16x16x32_bf16 v[2:5], v[194:197], v[238:241], v[2:5]
	s_barrier
	s_cmp_gt_u32 s91, 13
	s_cbranch_scc0 .LBB0_850
	s_setprio 0
	s_and_b64 vcc, exec, s[62:63]
	s_cbranch_vccz .LBB0_853
	s_barrier
